# on top of static-prio version: the two loop-invariant ds_read base-address VALU adds per K-loop iteration hoisted out of the loop into v246/v247
# baseline (speedup 1.0000x reference)
.Lsprio_0:
	v_add_u32_e32 v246, 0x18000, v155
	v_add_u32_e32 v247, 0x1c000, v155
.LBB0_1790:
	ds_read_b128 v[146:149], v159
	ds_read_b128 v[150:153], v159 offset:1024
	ds_read_b128 v[164:167], v159 offset:2048
	ds_read_b128 v[168:171], v159 offset:3072
	ds_read_b128 v[172:175], v160
	ds_read_b128 v[176:179], v160 offset:1024
	ds_read_b128 v[186:189], v160 offset:2048
	ds_read_b128 v[190:193], v160 offset:3072
	s_add_u32 s79, s6, 0xfff00080
	s_addc_u32 s80, s7, -1
	s_cmp_eq_u32 s78, 60
	s_cselect_b32 s91, s45, s80
	s_cselect_b32 s90, s74, s79
	s_cselect_b32 s89, s43, s77
	s_cselect_b32 s88, s75, s76
	s_add_i32 m0, s33, 0xc000
	ds_read_b128 v[194:197], v161
	ds_read_b128 v[198:201], v161 offset:1024
	ds_read_b128 v[202:205], v161 offset:2048
	ds_read_b128 v[206:209], v161 offset:3072
	ds_read_b128 v[210:213], v161 offset:4096
	ds_read_b128 v[214:217], v161 offset:5120
	ds_read_b128 v[218:221], v161 offset:6144
	ds_read_b128 v[222:225], v161 offset:7168
	global_load_lds_dwordx4 v138, s[6:7]
	s_add_i32 m0, s33, 0xe000
	s_nop 0
	global_load_lds_dwordx4 v140, s[6:7]
	s_waitcnt vmcnt(8)
	s_waitcnt lgkmcnt(0)
	s_barrier
	v_mfma_f32_16x16x32_bf16 v[126:129], v[146:149], v[194:197], v[126:129]
	v_mfma_f32_16x16x32_bf16 v[126:129], v[150:153], v[198:201], v[126:129]
	v_mfma_f32_16x16x32_bf16 v[122:125], v[164:167], v[194:197], v[122:125]
	v_mfma_f32_16x16x32_bf16 v[122:125], v[168:171], v[198:201], v[122:125]
	v_mfma_f32_16x16x32_bf16 v[118:121], v[172:175], v[194:197], v[118:121]
	v_mfma_f32_16x16x32_bf16 v[118:121], v[176:179], v[198:201], v[118:121]
	v_mfma_f32_16x16x32_bf16 v[110:113], v[186:189], v[194:197], v[110:113]
	v_mfma_f32_16x16x32_bf16 v[110:113], v[190:193], v[198:201], v[110:113]
	v_mfma_f32_16x16x32_bf16 v[114:117], v[146:149], v[202:205], v[114:117]
	v_mfma_f32_16x16x32_bf16 v[114:117], v[150:153], v[206:209], v[114:117]
	v_mfma_f32_16x16x32_bf16 v[106:109], v[164:167], v[202:205], v[106:109]
	v_mfma_f32_16x16x32_bf16 v[106:109], v[168:171], v[206:209], v[106:109]
	v_mfma_f32_16x16x32_bf16 v[102:105], v[172:175], v[202:205], v[102:105]
	v_mfma_f32_16x16x32_bf16 v[102:105], v[176:179], v[206:209], v[102:105]
	v_mfma_f32_16x16x32_bf16 v[94:97], v[186:189], v[202:205], v[94:97]
	v_mfma_f32_16x16x32_bf16 v[94:97], v[190:193], v[206:209], v[94:97]
	v_mfma_f32_16x16x32_bf16 v[98:101], v[146:149], v[210:213], v[98:101]
	v_mfma_f32_16x16x32_bf16 v[98:101], v[150:153], v[214:217], v[98:101]
	v_mfma_f32_16x16x32_bf16 v[90:93], v[164:167], v[210:213], v[90:93]
	v_mfma_f32_16x16x32_bf16 v[90:93], v[168:171], v[214:217], v[90:93]
	v_mfma_f32_16x16x32_bf16 v[86:89], v[172:175], v[210:213], v[86:89]
	v_mfma_f32_16x16x32_bf16 v[86:89], v[176:179], v[214:217], v[86:89]
	v_mfma_f32_16x16x32_bf16 v[78:81], v[186:189], v[210:213], v[78:81]
	v_mfma_f32_16x16x32_bf16 v[78:81], v[190:193], v[214:217], v[78:81]
	v_mfma_f32_16x16x32_bf16 v[82:85], v[146:149], v[218:221], v[82:85]
	v_mfma_f32_16x16x32_bf16 v[82:85], v[150:153], v[222:225], v[82:85]
	v_mfma_f32_16x16x32_bf16 v[74:77], v[164:167], v[218:221], v[74:77]
	v_mfma_f32_16x16x32_bf16 v[74:77], v[168:171], v[222:225], v[74:77]
	v_mfma_f32_16x16x32_bf16 v[70:73], v[172:175], v[218:221], v[70:73]
	v_mfma_f32_16x16x32_bf16 v[70:73], v[176:179], v[222:225], v[70:73]
	v_mfma_f32_16x16x32_bf16 v[66:69], v[186:189], v[218:221], v[66:69]
	v_mfma_f32_16x16x32_bf16 v[66:69], v[190:193], v[222:225], v[66:69]
	s_barrier
	s_add_i32 s79, s69, s25
	s_add_u32 s98, s88, 0x80
	s_addc_u32 s99, s89, 0
	s_mov_b32 m0, s79
	ds_read_b128 v[194:197], v161 offset:16384
	ds_read_b128 v[198:201], v161 offset:17408
	ds_read_b128 v[202:205], v161 offset:18432
	ds_read_b128 v[206:209], v161 offset:19456
	ds_read_b128 v[210:213], v161 offset:20480
	ds_read_b128 v[214:217], v161 offset:21504
	ds_read_b128 v[218:221], v161 offset:22528
	ds_read_b128 v[222:225], v161 offset:23552
	global_load_lds_dwordx4 v132, s[88:89]
	s_add_i32 m0, s79, 0x2000
	s_add_u32 s80, s88, 0x100000
	s_addc_u32 s81, s89, 0
	s_add_i32 s79, s70, s25
	global_load_lds_dwordx4 v136, s[88:89]
	s_mov_b32 m0, s79
	global_load_lds_dwordx4 v132, s[80:81]
	s_add_i32 m0, s79, 0x2000
	s_nop 0
	global_load_lds_dwordx4 v136, s[80:81]
	s_add_u32 s100, s90, 0x80
	s_addc_u32 s101, s91, 0
	s_mov_b32 m0, s33
	s_nop 0
	global_load_lds_dwordx4 v130, s[90:91]
	s_mov_b32 m0, s35
	s_nop 0
	global_load_lds_dwordx4 v134, s[90:91]
	s_waitcnt vmcnt(8)
	s_waitcnt lgkmcnt(0)
	s_barrier
	v_mfma_f32_16x16x32_bf16 v[62:65], v[146:149], v[194:197], v[62:65]
	v_mfma_f32_16x16x32_bf16 v[62:65], v[150:153], v[198:201], v[62:65]
	v_mfma_f32_16x16x32_bf16 v[58:61], v[164:167], v[194:197], v[58:61]
	v_mfma_f32_16x16x32_bf16 v[58:61], v[168:171], v[198:201], v[58:61]
	v_mfma_f32_16x16x32_bf16 v[54:57], v[172:175], v[194:197], v[54:57]
	v_mfma_f32_16x16x32_bf16 v[54:57], v[176:179], v[198:201], v[54:57]
	v_mfma_f32_16x16x32_bf16 v[46:49], v[186:189], v[194:197], v[46:49]
	v_mfma_f32_16x16x32_bf16 v[46:49], v[190:193], v[198:201], v[46:49]
	v_mfma_f32_16x16x32_bf16 v[50:53], v[146:149], v[202:205], v[50:53]
	v_mfma_f32_16x16x32_bf16 v[50:53], v[150:153], v[206:209], v[50:53]
	v_mfma_f32_16x16x32_bf16 v[42:45], v[164:167], v[202:205], v[42:45]
	v_mfma_f32_16x16x32_bf16 v[42:45], v[168:171], v[206:209], v[42:45]
	v_mfma_f32_16x16x32_bf16 v[38:41], v[172:175], v[202:205], v[38:41]
	v_mfma_f32_16x16x32_bf16 v[38:41], v[176:179], v[206:209], v[38:41]
	v_mfma_f32_16x16x32_bf16 v[30:33], v[186:189], v[202:205], v[30:33]
	v_mfma_f32_16x16x32_bf16 v[30:33], v[190:193], v[206:209], v[30:33]
	v_mfma_f32_16x16x32_bf16 v[34:37], v[146:149], v[210:213], v[34:37]
	v_mfma_f32_16x16x32_bf16 v[34:37], v[150:153], v[214:217], v[34:37]
	v_mfma_f32_16x16x32_bf16 v[26:29], v[164:167], v[210:213], v[26:29]
	v_mfma_f32_16x16x32_bf16 v[26:29], v[168:171], v[214:217], v[26:29]
	v_mfma_f32_16x16x32_bf16 v[22:25], v[172:175], v[210:213], v[22:25]
	v_mfma_f32_16x16x32_bf16 v[22:25], v[176:179], v[214:217], v[22:25]
	v_mfma_f32_16x16x32_bf16 v[14:17], v[186:189], v[210:213], v[14:17]
	v_mfma_f32_16x16x32_bf16 v[14:17], v[190:193], v[214:217], v[14:17]
	v_mfma_f32_16x16x32_bf16 v[18:21], v[146:149], v[218:221], v[18:21]
	v_mfma_f32_16x16x32_bf16 v[18:21], v[150:153], v[222:225], v[18:21]
	v_mfma_f32_16x16x32_bf16 v[10:13], v[164:167], v[218:221], v[10:13]
	v_mfma_f32_16x16x32_bf16 v[10:13], v[168:171], v[222:225], v[10:13]
	v_mfma_f32_16x16x32_bf16 v[6:9], v[172:175], v[218:221], v[6:9]
	v_mfma_f32_16x16x32_bf16 v[6:9], v[176:179], v[222:225], v[6:9]
	v_mfma_f32_16x16x32_bf16 v[2:5], v[186:189], v[218:221], v[2:5]
	v_mfma_f32_16x16x32_bf16 v[2:5], v[190:193], v[222:225], v[2:5]
	s_barrier
	s_add_i32 s79, 0, 0x18000
	s_add_i32 s82, 0, 0x1c000
	ds_read_b128 v[146:149], v246
	ds_read_b128 v[150:153], v246 offset:1024
	ds_read_b128 v[164:167], v246 offset:2048
	ds_read_b128 v[168:171], v246 offset:3072
	ds_read_b128 v[172:175], v247
	ds_read_b128 v[176:179], v247 offset:1024
	ds_read_b128 v[186:189], v247 offset:2048
	ds_read_b128 v[190:193], v247 offset:3072
	s_add_u32 s80, s90, 0x100000
	s_addc_u32 s81, s91, 0
	s_mov_b32 m0, s59
	ds_read_b128 v[194:197], v161 offset:32768
	ds_read_b128 v[198:201], v161 offset:33792
	ds_read_b128 v[202:205], v161 offset:34816
	ds_read_b128 v[206:209], v161 offset:35840
	ds_read_b128 v[210:213], v161 offset:36864
	ds_read_b128 v[214:217], v161 offset:37888
	ds_read_b128 v[218:221], v161 offset:38912
	ds_read_b128 v[222:225], v161 offset:39936
	global_load_lds_dwordx4 v130, s[80:81]
	s_mov_b32 m0, s62
	s_nop 0
	global_load_lds_dwordx4 v134, s[80:81]
	s_waitcnt vmcnt(8)
	s_waitcnt lgkmcnt(0)
	s_barrier
	v_mfma_f32_16x16x32_bf16 v[126:129], v[146:149], v[194:197], v[126:129]
	v_mfma_f32_16x16x32_bf16 v[126:129], v[150:153], v[198:201], v[126:129]
	v_mfma_f32_16x16x32_bf16 v[122:125], v[164:167], v[194:197], v[122:125]
	v_mfma_f32_16x16x32_bf16 v[122:125], v[168:171], v[198:201], v[122:125]
	v_mfma_f32_16x16x32_bf16 v[118:121], v[172:175], v[194:197], v[118:121]
	v_mfma_f32_16x16x32_bf16 v[118:121], v[176:179], v[198:201], v[118:121]
	v_mfma_f32_16x16x32_bf16 v[110:113], v[186:189], v[194:197], v[110:113]
	v_mfma_f32_16x16x32_bf16 v[110:113], v[190:193], v[198:201], v[110:113]
	v_mfma_f32_16x16x32_bf16 v[114:117], v[146:149], v[202:205], v[114:117]
	v_mfma_f32_16x16x32_bf16 v[114:117], v[150:153], v[206:209], v[114:117]
	v_mfma_f32_16x16x32_bf16 v[106:109], v[164:167], v[202:205], v[106:109]
	v_mfma_f32_16x16x32_bf16 v[106:109], v[168:171], v[206:209], v[106:109]
	v_mfma_f32_16x16x32_bf16 v[102:105], v[172:175], v[202:205], v[102:105]
	v_mfma_f32_16x16x32_bf16 v[102:105], v[176:179], v[206:209], v[102:105]
	v_mfma_f32_16x16x32_bf16 v[94:97], v[186:189], v[202:205], v[94:97]
	v_mfma_f32_16x16x32_bf16 v[94:97], v[190:193], v[206:209], v[94:97]
	v_mfma_f32_16x16x32_bf16 v[98:101], v[146:149], v[210:213], v[98:101]
	v_mfma_f32_16x16x32_bf16 v[98:101], v[150:153], v[214:217], v[98:101]
	v_mfma_f32_16x16x32_bf16 v[90:93], v[164:167], v[210:213], v[90:93]
	v_mfma_f32_16x16x32_bf16 v[90:93], v[168:171], v[214:217], v[90:93]
	v_mfma_f32_16x16x32_bf16 v[86:89], v[172:175], v[210:213], v[86:89]
	v_mfma_f32_16x16x32_bf16 v[86:89], v[176:179], v[214:217], v[86:89]
	v_mfma_f32_16x16x32_bf16 v[78:81], v[186:189], v[210:213], v[78:81]
	v_mfma_f32_16x16x32_bf16 v[78:81], v[190:193], v[214:217], v[78:81]
	v_mfma_f32_16x16x32_bf16 v[82:85], v[146:149], v[218:221], v[82:85]
	v_mfma_f32_16x16x32_bf16 v[82:85], v[150:153], v[222:225], v[82:85]
	v_mfma_f32_16x16x32_bf16 v[74:77], v[164:167], v[218:221], v[74:77]
	v_mfma_f32_16x16x32_bf16 v[74:77], v[168:171], v[222:225], v[74:77]
	v_mfma_f32_16x16x32_bf16 v[70:73], v[172:175], v[218:221], v[70:73]
	v_mfma_f32_16x16x32_bf16 v[70:73], v[176:179], v[222:225], v[70:73]
	v_mfma_f32_16x16x32_bf16 v[66:69], v[186:189], v[218:221], v[66:69]
	v_mfma_f32_16x16x32_bf16 v[66:69], v[190:193], v[222:225], v[66:69]
	s_barrier
	s_add_i32 s79, s79, s25
	s_mov_b32 m0, s79
	ds_read_b128 v[194:197], v161 offset:49152
	ds_read_b128 v[198:201], v161 offset:50176
	ds_read_b128 v[202:205], v161 offset:51200
	ds_read_b128 v[206:209], v161 offset:52224
	ds_read_b128 v[210:213], v161 offset:53248
	ds_read_b128 v[214:217], v161 offset:54272
	ds_read_b128 v[218:221], v161 offset:55296
	ds_read_b128 v[222:225], v161 offset:56320
	global_load_lds_dwordx4 v132, s[98:99]
	s_add_i32 m0, s79, 0x2000
	s_add_u32 s80, s88, 0x100080
	s_addc_u32 s81, s89, 0
	s_add_i32 s79, s82, s25
	global_load_lds_dwordx4 v136, s[98:99]
	s_mov_b32 m0, s79
	s_nop 0
	global_load_lds_dwordx4 v132, s[80:81]
	s_add_i32 m0, s79, 0x2000
	s_nop 0
	global_load_lds_dwordx4 v136, s[80:81]
	s_mov_b32 m0, s66
	s_nop 0
	global_load_lds_dwordx4 v130, s[100:101]
	s_mov_b32 m0, s67
	s_nop 0
	global_load_lds_dwordx4 v134, s[100:101]
	s_waitcnt vmcnt(8)
	s_waitcnt lgkmcnt(0)
	s_barrier
	v_mfma_f32_16x16x32_bf16 v[62:65], v[146:149], v[194:197], v[62:65]
	v_mfma_f32_16x16x32_bf16 v[62:65], v[150:153], v[198:201], v[62:65]
	v_mfma_f32_16x16x32_bf16 v[58:61], v[164:167], v[194:197], v[58:61]
	v_mfma_f32_16x16x32_bf16 v[58:61], v[168:171], v[198:201], v[58:61]
	v_mfma_f32_16x16x32_bf16 v[54:57], v[172:175], v[194:197], v[54:57]
	v_mfma_f32_16x16x32_bf16 v[54:57], v[176:179], v[198:201], v[54:57]
	v_mfma_f32_16x16x32_bf16 v[46:49], v[186:189], v[194:197], v[46:49]
	v_mfma_f32_16x16x32_bf16 v[46:49], v[190:193], v[198:201], v[46:49]
	v_mfma_f32_16x16x32_bf16 v[50:53], v[146:149], v[202:205], v[50:53]
	v_mfma_f32_16x16x32_bf16 v[50:53], v[150:153], v[206:209], v[50:53]
	v_mfma_f32_16x16x32_bf16 v[42:45], v[164:167], v[202:205], v[42:45]
	v_mfma_f32_16x16x32_bf16 v[42:45], v[168:171], v[206:209], v[42:45]
	v_mfma_f32_16x16x32_bf16 v[38:41], v[172:175], v[202:205], v[38:41]
	v_mfma_f32_16x16x32_bf16 v[38:41], v[176:179], v[206:209], v[38:41]
	v_mfma_f32_16x16x32_bf16 v[30:33], v[186:189], v[202:205], v[30:33]
	v_mfma_f32_16x16x32_bf16 v[30:33], v[190:193], v[206:209], v[30:33]
	v_mfma_f32_16x16x32_bf16 v[34:37], v[146:149], v[210:213], v[34:37]
	v_mfma_f32_16x16x32_bf16 v[34:37], v[150:153], v[214:217], v[34:37]
	v_mfma_f32_16x16x32_bf16 v[26:29], v[164:167], v[210:213], v[26:29]
	v_mfma_f32_16x16x32_bf16 v[26:29], v[168:171], v[214:217], v[26:29]
	v_mfma_f32_16x16x32_bf16 v[22:25], v[172:175], v[210:213], v[22:25]
	v_mfma_f32_16x16x32_bf16 v[22:25], v[176:179], v[214:217], v[22:25]
	v_mfma_f32_16x16x32_bf16 v[14:17], v[186:189], v[210:213], v[14:17]
	v_mfma_f32_16x16x32_bf16 v[14:17], v[190:193], v[214:217], v[14:17]
	v_mfma_f32_16x16x32_bf16 v[18:21], v[146:149], v[218:221], v[18:21]
	v_mfma_f32_16x16x32_bf16 v[18:21], v[150:153], v[222:225], v[18:21]
	v_mfma_f32_16x16x32_bf16 v[10:13], v[164:167], v[218:221], v[10:13]
	v_mfma_f32_16x16x32_bf16 v[10:13], v[168:171], v[222:225], v[10:13]
	v_mfma_f32_16x16x32_bf16 v[6:9], v[172:175], v[218:221], v[6:9]
	v_mfma_f32_16x16x32_bf16 v[6:9], v[176:179], v[222:225], v[6:9]
	v_mfma_f32_16x16x32_bf16 v[2:5], v[186:189], v[218:221], v[2:5]
	v_mfma_f32_16x16x32_bf16 v[2:5], v[190:193], v[222:225], v[2:5]
	s_barrier
	s_add_i32 s78, s78, 2
	s_add_u32 s6, s6, 0x100
	s_addc_u32 s7, s7, 0
	s_add_u32 s76, s76, 0x100
	s_addc_u32 s77, s77, 0
	s_cmp_gt_u32 s78, 61
	s_cbranch_scc0 .LBB0_1790
	s_setprio 0
	s_and_b64 vcc, exec, s[40:41]
	s_cbranch_vccz .LBB0_1793
	s_barrier

.Lsprio_1:
	v_add_u32_e32 v246, 0x18000, v174
	v_add_u32_e32 v247, 0x1c000, v174
.LBB0_2109:
	ds_read_b128 v[130:133], v155
	ds_read_b128 v[134:137], v155 offset:1024
	ds_read_b128 v[138:141], v155 offset:2048
	ds_read_b128 v[142:145], v155 offset:3072
	ds_read_b128 v[166:169], v176
	ds_read_b128 v[170:173], v176 offset:1024
	ds_read_b128 v[186:189], v176 offset:2048
	ds_read_b128 v[190:193], v176 offset:3072
	s_add_u32 s74, s50, 0xfff00080
	s_addc_u32 s75, s51, -1
	s_cmp_eq_u32 s73, 60
	s_cselect_b32 s85, s26, s75
	s_cselect_b32 s84, s45, s74
	s_cselect_b32 s83, s43, s72
	s_cselect_b32 s82, s70, s71
	s_add_i32 m0, s23, 0xc000
	ds_read_b128 v[194:197], v177
	ds_read_b128 v[198:201], v177 offset:1024
	ds_read_b128 v[202:205], v177 offset:2048
	ds_read_b128 v[206:209], v177 offset:3072
	ds_read_b128 v[210:213], v177 offset:4096
	ds_read_b128 v[214:217], v177 offset:5120
	ds_read_b128 v[218:221], v177 offset:6144
	ds_read_b128 v[222:225], v177 offset:7168
	global_load_lds_dwordx4 v158, s[50:51]
	s_add_i32 m0, s23, 0xe000
	s_nop 0
	global_load_lds_dwordx4 v160, s[50:51]
	s_waitcnt vmcnt(8)
	s_waitcnt lgkmcnt(0)
	s_barrier
	v_mfma_f32_16x16x32_bf16 v[126:129], v[130:133], v[194:197], v[126:129]
	v_mfma_f32_16x16x32_bf16 v[126:129], v[134:137], v[198:201], v[126:129]
	v_mfma_f32_16x16x32_bf16 v[122:125], v[138:141], v[194:197], v[122:125]
	v_mfma_f32_16x16x32_bf16 v[122:125], v[142:145], v[198:201], v[122:125]
	v_mfma_f32_16x16x32_bf16 v[118:121], v[166:169], v[194:197], v[118:121]
	v_mfma_f32_16x16x32_bf16 v[118:121], v[170:173], v[198:201], v[118:121]
	v_mfma_f32_16x16x32_bf16 v[114:117], v[186:189], v[194:197], v[114:117]
	v_mfma_f32_16x16x32_bf16 v[114:117], v[190:193], v[198:201], v[114:117]
	v_mfma_f32_16x16x32_bf16 v[110:113], v[130:133], v[202:205], v[110:113]
	v_mfma_f32_16x16x32_bf16 v[110:113], v[134:137], v[206:209], v[110:113]
	v_mfma_f32_16x16x32_bf16 v[106:109], v[138:141], v[202:205], v[106:109]
	v_mfma_f32_16x16x32_bf16 v[106:109], v[142:145], v[206:209], v[106:109]
	v_mfma_f32_16x16x32_bf16 v[102:105], v[166:169], v[202:205], v[102:105]
	v_mfma_f32_16x16x32_bf16 v[102:105], v[170:173], v[206:209], v[102:105]
	v_mfma_f32_16x16x32_bf16 v[98:101], v[186:189], v[202:205], v[98:101]
	v_mfma_f32_16x16x32_bf16 v[98:101], v[190:193], v[206:209], v[98:101]
	v_mfma_f32_16x16x32_bf16 v[94:97], v[130:133], v[210:213], v[94:97]
	v_mfma_f32_16x16x32_bf16 v[94:97], v[134:137], v[214:217], v[94:97]
	v_mfma_f32_16x16x32_bf16 v[90:93], v[138:141], v[210:213], v[90:93]
	v_mfma_f32_16x16x32_bf16 v[90:93], v[142:145], v[214:217], v[90:93]
	v_mfma_f32_16x16x32_bf16 v[86:89], v[166:169], v[210:213], v[86:89]
	v_mfma_f32_16x16x32_bf16 v[86:89], v[170:173], v[214:217], v[86:89]
	v_mfma_f32_16x16x32_bf16 v[82:85], v[186:189], v[210:213], v[82:85]
	v_mfma_f32_16x16x32_bf16 v[82:85], v[190:193], v[214:217], v[82:85]
	v_mfma_f32_16x16x32_bf16 v[78:81], v[130:133], v[218:221], v[78:81]
	v_mfma_f32_16x16x32_bf16 v[78:81], v[134:137], v[222:225], v[78:81]
	v_mfma_f32_16x16x32_bf16 v[74:77], v[138:141], v[218:221], v[74:77]
	v_mfma_f32_16x16x32_bf16 v[74:77], v[142:145], v[222:225], v[74:77]
	v_mfma_f32_16x16x32_bf16 v[70:73], v[166:169], v[218:221], v[70:73]
	v_mfma_f32_16x16x32_bf16 v[70:73], v[170:173], v[222:225], v[70:73]
	v_mfma_f32_16x16x32_bf16 v[66:69], v[186:189], v[218:221], v[66:69]
	v_mfma_f32_16x16x32_bf16 v[66:69], v[190:193], v[222:225], v[66:69]
	s_barrier
	s_add_i32 s74, s67, s3
	s_add_u32 s98, s82, 0x80
	s_addc_u32 s99, s83, 0
	s_mov_b32 m0, s74
	ds_read_b128 v[194:197], v177 offset:16384
	ds_read_b128 v[198:201], v177 offset:17408
	ds_read_b128 v[202:205], v177 offset:18432
	ds_read_b128 v[206:209], v177 offset:19456
	ds_read_b128 v[210:213], v177 offset:20480
	ds_read_b128 v[214:217], v177 offset:21504
	ds_read_b128 v[218:221], v177 offset:22528
	ds_read_b128 v[222:225], v177 offset:23552
	global_load_lds_dwordx4 v148, s[82:83]
	s_add_i32 m0, s74, 0x2000
	s_add_u32 s74, s82, 0x100000
	s_addc_u32 s75, s83, 0
	s_add_i32 s76, s68, s3
	global_load_lds_dwordx4 v152, s[82:83]
	s_mov_b32 m0, s76
	global_load_lds_dwordx4 v148, s[74:75]
	s_add_i32 m0, s76, 0x2000
	s_nop 0
	global_load_lds_dwordx4 v152, s[74:75]
	s_add_u32 s100, s84, 0x80
	s_addc_u32 s101, s85, 0
	s_mov_b32 m0, s23
	s_nop 0
	global_load_lds_dwordx4 v146, s[84:85]
	s_mov_b32 m0, s25
	s_nop 0
	global_load_lds_dwordx4 v150, s[84:85]
	s_waitcnt vmcnt(8)
	s_waitcnt lgkmcnt(0)
	s_barrier
	v_mfma_f32_16x16x32_bf16 v[62:65], v[130:133], v[194:197], v[62:65]
	v_mfma_f32_16x16x32_bf16 v[62:65], v[134:137], v[198:201], v[62:65]
	v_mfma_f32_16x16x32_bf16 v[58:61], v[138:141], v[194:197], v[58:61]
	v_mfma_f32_16x16x32_bf16 v[58:61], v[142:145], v[198:201], v[58:61]
	v_mfma_f32_16x16x32_bf16 v[54:57], v[166:169], v[194:197], v[54:57]
	v_mfma_f32_16x16x32_bf16 v[54:57], v[170:173], v[198:201], v[54:57]
	v_mfma_f32_16x16x32_bf16 v[50:53], v[186:189], v[194:197], v[50:53]
	v_mfma_f32_16x16x32_bf16 v[50:53], v[190:193], v[198:201], v[50:53]
	v_mfma_f32_16x16x32_bf16 v[46:49], v[130:133], v[202:205], v[46:49]
	v_mfma_f32_16x16x32_bf16 v[46:49], v[134:137], v[206:209], v[46:49]
	v_mfma_f32_16x16x32_bf16 v[42:45], v[138:141], v[202:205], v[42:45]
	v_mfma_f32_16x16x32_bf16 v[42:45], v[142:145], v[206:209], v[42:45]
	v_mfma_f32_16x16x32_bf16 v[38:41], v[166:169], v[202:205], v[38:41]
	v_mfma_f32_16x16x32_bf16 v[38:41], v[170:173], v[206:209], v[38:41]
	v_mfma_f32_16x16x32_bf16 v[34:37], v[186:189], v[202:205], v[34:37]
	v_mfma_f32_16x16x32_bf16 v[34:37], v[190:193], v[206:209], v[34:37]
	v_mfma_f32_16x16x32_bf16 v[30:33], v[130:133], v[210:213], v[30:33]
	v_mfma_f32_16x16x32_bf16 v[30:33], v[134:137], v[214:217], v[30:33]
	v_mfma_f32_16x16x32_bf16 v[26:29], v[138:141], v[210:213], v[26:29]
	v_mfma_f32_16x16x32_bf16 v[26:29], v[142:145], v[214:217], v[26:29]
	v_mfma_f32_16x16x32_bf16 v[22:25], v[166:169], v[210:213], v[22:25]
	v_mfma_f32_16x16x32_bf16 v[22:25], v[170:173], v[214:217], v[22:25]
	v_mfma_f32_16x16x32_bf16 v[18:21], v[186:189], v[210:213], v[18:21]
	v_mfma_f32_16x16x32_bf16 v[18:21], v[190:193], v[214:217], v[18:21]
	v_mfma_f32_16x16x32_bf16 v[14:17], v[130:133], v[218:221], v[14:17]
	v_mfma_f32_16x16x32_bf16 v[14:17], v[134:137], v[222:225], v[14:17]
	v_mfma_f32_16x16x32_bf16 v[10:13], v[138:141], v[218:221], v[10:13]
	v_mfma_f32_16x16x32_bf16 v[10:13], v[142:145], v[222:225], v[10:13]
	v_mfma_f32_16x16x32_bf16 v[6:9], v[166:169], v[218:221], v[6:9]
	v_mfma_f32_16x16x32_bf16 v[6:9], v[170:173], v[222:225], v[6:9]
	v_mfma_f32_16x16x32_bf16 v[2:5], v[186:189], v[218:221], v[2:5]
	v_mfma_f32_16x16x32_bf16 v[2:5], v[190:193], v[222:225], v[2:5]
	s_barrier
	s_add_i32 s76, 0, 0x18000
	s_add_i32 s77, 0, 0x1c000
	ds_read_b128 v[130:133], v246
	ds_read_b128 v[134:137], v246 offset:1024
	ds_read_b128 v[138:141], v246 offset:2048
	ds_read_b128 v[142:145], v246 offset:3072
	ds_read_b128 v[166:169], v247
	ds_read_b128 v[170:173], v247 offset:1024
	ds_read_b128 v[186:189], v247 offset:2048
	ds_read_b128 v[190:193], v247 offset:3072
	s_add_u32 s74, s84, 0x100000
	s_addc_u32 s75, s85, 0
	s_mov_b32 m0, s33
	ds_read_b128 v[194:197], v177 offset:32768
	ds_read_b128 v[198:201], v177 offset:33792
	ds_read_b128 v[202:205], v177 offset:34816
	ds_read_b128 v[206:209], v177 offset:35840
	ds_read_b128 v[210:213], v177 offset:36864
	ds_read_b128 v[214:217], v177 offset:37888
	ds_read_b128 v[218:221], v177 offset:38912
	ds_read_b128 v[222:225], v177 offset:39936
	global_load_lds_dwordx4 v146, s[74:75]
	s_mov_b32 m0, s35
	s_nop 0
	global_load_lds_dwordx4 v150, s[74:75]
	s_waitcnt vmcnt(8)
	s_waitcnt lgkmcnt(0)
	s_barrier
	v_mfma_f32_16x16x32_bf16 v[126:129], v[130:133], v[194:197], v[126:129]
	v_mfma_f32_16x16x32_bf16 v[126:129], v[134:137], v[198:201], v[126:129]
	v_mfma_f32_16x16x32_bf16 v[122:125], v[138:141], v[194:197], v[122:125]
	v_mfma_f32_16x16x32_bf16 v[122:125], v[142:145], v[198:201], v[122:125]
	v_mfma_f32_16x16x32_bf16 v[118:121], v[166:169], v[194:197], v[118:121]
	v_mfma_f32_16x16x32_bf16 v[118:121], v[170:173], v[198:201], v[118:121]
	v_mfma_f32_16x16x32_bf16 v[114:117], v[186:189], v[194:197], v[114:117]
	v_mfma_f32_16x16x32_bf16 v[114:117], v[190:193], v[198:201], v[114:117]
	v_mfma_f32_16x16x32_bf16 v[110:113], v[130:133], v[202:205], v[110:113]
	v_mfma_f32_16x16x32_bf16 v[110:113], v[134:137], v[206:209], v[110:113]
	v_mfma_f32_16x16x32_bf16 v[106:109], v[138:141], v[202:205], v[106:109]
	v_mfma_f32_16x16x32_bf16 v[106:109], v[142:145], v[206:209], v[106:109]
	v_mfma_f32_16x16x32_bf16 v[102:105], v[166:169], v[202:205], v[102:105]
	v_mfma_f32_16x16x32_bf16 v[102:105], v[170:173], v[206:209], v[102:105]
	v_mfma_f32_16x16x32_bf16 v[98:101], v[186:189], v[202:205], v[98:101]
	v_mfma_f32_16x16x32_bf16 v[98:101], v[190:193], v[206:209], v[98:101]
	v_mfma_f32_16x16x32_bf16 v[94:97], v[130:133], v[210:213], v[94:97]
	v_mfma_f32_16x16x32_bf16 v[94:97], v[134:137], v[214:217], v[94:97]
	v_mfma_f32_16x16x32_bf16 v[90:93], v[138:141], v[210:213], v[90:93]
	v_mfma_f32_16x16x32_bf16 v[90:93], v[142:145], v[214:217], v[90:93]
	v_mfma_f32_16x16x32_bf16 v[86:89], v[166:169], v[210:213], v[86:89]
	v_mfma_f32_16x16x32_bf16 v[86:89], v[170:173], v[214:217], v[86:89]
	v_mfma_f32_16x16x32_bf16 v[82:85], v[186:189], v[210:213], v[82:85]
	v_mfma_f32_16x16x32_bf16 v[82:85], v[190:193], v[214:217], v[82:85]
	v_mfma_f32_16x16x32_bf16 v[78:81], v[130:133], v[218:221], v[78:81]
	v_mfma_f32_16x16x32_bf16 v[78:81], v[134:137], v[222:225], v[78:81]
	v_mfma_f32_16x16x32_bf16 v[74:77], v[138:141], v[218:221], v[74:77]
	v_mfma_f32_16x16x32_bf16 v[74:77], v[142:145], v[222:225], v[74:77]
	v_mfma_f32_16x16x32_bf16 v[70:73], v[166:169], v[218:221], v[70:73]
	v_mfma_f32_16x16x32_bf16 v[70:73], v[170:173], v[222:225], v[70:73]
	v_mfma_f32_16x16x32_bf16 v[66:69], v[186:189], v[218:221], v[66:69]
	v_mfma_f32_16x16x32_bf16 v[66:69], v[190:193], v[222:225], v[66:69]
	s_barrier
	s_add_i32 s74, s76, s3
	s_mov_b32 m0, s74
	ds_read_b128 v[194:197], v177 offset:49152
	ds_read_b128 v[198:201], v177 offset:50176
	ds_read_b128 v[202:205], v177 offset:51200
	ds_read_b128 v[206:209], v177 offset:52224
	ds_read_b128 v[210:213], v177 offset:53248
	ds_read_b128 v[214:217], v177 offset:54272
	ds_read_b128 v[218:221], v177 offset:55296
	ds_read_b128 v[222:225], v177 offset:56320
	global_load_lds_dwordx4 v148, s[98:99]
	s_add_i32 m0, s74, 0x2000
	s_add_u32 s74, s82, 0x100080
	s_addc_u32 s75, s83, 0
	s_add_i32 s76, s77, s3
	global_load_lds_dwordx4 v152, s[98:99]
	s_mov_b32 m0, s76
	s_nop 0
	global_load_lds_dwordx4 v148, s[74:75]
	s_add_i32 m0, s76, 0x2000
	s_nop 0
	global_load_lds_dwordx4 v152, s[74:75]
	s_mov_b32 m0, s62
	s_nop 0
	global_load_lds_dwordx4 v146, s[100:101]
	s_mov_b32 m0, s63
	s_nop 0
	global_load_lds_dwordx4 v150, s[100:101]
	s_waitcnt vmcnt(8)
	s_waitcnt lgkmcnt(0)
	s_barrier
	v_mfma_f32_16x16x32_bf16 v[62:65], v[130:133], v[194:197], v[62:65]
	v_mfma_f32_16x16x32_bf16 v[62:65], v[134:137], v[198:201], v[62:65]
	v_mfma_f32_16x16x32_bf16 v[58:61], v[138:141], v[194:197], v[58:61]
	v_mfma_f32_16x16x32_bf16 v[58:61], v[142:145], v[198:201], v[58:61]
	v_mfma_f32_16x16x32_bf16 v[54:57], v[166:169], v[194:197], v[54:57]
	v_mfma_f32_16x16x32_bf16 v[54:57], v[170:173], v[198:201], v[54:57]
	v_mfma_f32_16x16x32_bf16 v[50:53], v[186:189], v[194:197], v[50:53]
	v_mfma_f32_16x16x32_bf16 v[50:53], v[190:193], v[198:201], v[50:53]
	v_mfma_f32_16x16x32_bf16 v[46:49], v[130:133], v[202:205], v[46:49]
	v_mfma_f32_16x16x32_bf16 v[46:49], v[134:137], v[206:209], v[46:49]
	v_mfma_f32_16x16x32_bf16 v[42:45], v[138:141], v[202:205], v[42:45]
	v_mfma_f32_16x16x32_bf16 v[42:45], v[142:145], v[206:209], v[42:45]
	v_mfma_f32_16x16x32_bf16 v[38:41], v[166:169], v[202:205], v[38:41]
	v_mfma_f32_16x16x32_bf16 v[38:41], v[170:173], v[206:209], v[38:41]
	v_mfma_f32_16x16x32_bf16 v[34:37], v[186:189], v[202:205], v[34:37]
	v_mfma_f32_16x16x32_bf16 v[34:37], v[190:193], v[206:209], v[34:37]
	v_mfma_f32_16x16x32_bf16 v[30:33], v[130:133], v[210:213], v[30:33]
	v_mfma_f32_16x16x32_bf16 v[30:33], v[134:137], v[214:217], v[30:33]
	v_mfma_f32_16x16x32_bf16 v[26:29], v[138:141], v[210:213], v[26:29]
	v_mfma_f32_16x16x32_bf16 v[26:29], v[142:145], v[214:217], v[26:29]
	v_mfma_f32_16x16x32_bf16 v[22:25], v[166:169], v[210:213], v[22:25]
	v_mfma_f32_16x16x32_bf16 v[22:25], v[170:173], v[214:217], v[22:25]
	v_mfma_f32_16x16x32_bf16 v[18:21], v[186:189], v[210:213], v[18:21]
	v_mfma_f32_16x16x32_bf16 v[18:21], v[190:193], v[214:217], v[18:21]
	v_mfma_f32_16x16x32_bf16 v[14:17], v[130:133], v[218:221], v[14:17]
	v_mfma_f32_16x16x32_bf16 v[14:17], v[134:137], v[222:225], v[14:17]
	v_mfma_f32_16x16x32_bf16 v[10:13], v[138:141], v[218:221], v[10:13]
	v_mfma_f32_16x16x32_bf16 v[10:13], v[142:145], v[222:225], v[10:13]
	v_mfma_f32_16x16x32_bf16 v[6:9], v[166:169], v[218:221], v[6:9]
	v_mfma_f32_16x16x32_bf16 v[6:9], v[170:173], v[222:225], v[6:9]
	v_mfma_f32_16x16x32_bf16 v[2:5], v[186:189], v[218:221], v[2:5]
	v_mfma_f32_16x16x32_bf16 v[2:5], v[190:193], v[222:225], v[2:5]
	s_barrier
	s_add_i32 s73, s73, 2
	s_add_u32 s50, s50, 0x100
	s_addc_u32 s51, s51, 0
	s_add_u32 s71, s71, 0x100
	s_addc_u32 s72, s72, 0
	s_cmp_gt_u32 s73, 61
	s_cbranch_scc0 .LBB0_2109
	s_setprio 0
	s_and_b64 vcc, exec, s[40:41]
	s_cbranch_vccz .LBB0_2112
	s_barrier

.Lsprio_2:
	v_add_u32_e32 v246, 0x18000, v158
	v_add_u32_e32 v247, 0x1c000, v158
.LBB0_2212:
	ds_read_b128 v[150:153], v162
	ds_read_b128 v[168:171], v162 offset:1024
	ds_read_b128 v[172:175], v162 offset:2048
	ds_read_b128 v[176:179], v162 offset:3072
	ds_read_b128 v[186:189], v163
	ds_read_b128 v[190:193], v163 offset:1024
	ds_read_b128 v[194:197], v163 offset:2048
	ds_read_b128 v[198:201], v163 offset:3072
	s_add_u32 s50, s6, 0xfff00080
	s_addc_u32 s51, s7, -1
	s_cmp_eq_u32 s79, 60
	s_cselect_b32 s81, s45, s51
	s_cselect_b32 s80, s75, s50
	s_cselect_b32 s51, s43, s78
	s_cselect_b32 s50, s76, s77
	s_add_i32 m0, s33, 0xc000
	ds_read_b128 v[202:205], v164
	ds_read_b128 v[206:209], v164 offset:1024
	ds_read_b128 v[210:213], v164 offset:2048
	ds_read_b128 v[214:217], v164 offset:3072
	ds_read_b128 v[218:221], v164 offset:4096
	ds_read_b128 v[222:225], v164 offset:5120
	ds_read_b128 v[226:229], v164 offset:6144
	ds_read_b128 v[230:233], v164 offset:7168
	global_load_lds_dwordx4 v142, s[6:7]
	s_add_i32 m0, s33, 0xe000
	s_nop 0
	global_load_lds_dwordx4 v144, s[6:7]
	s_waitcnt vmcnt(8)
	s_waitcnt lgkmcnt(0)
	s_barrier
	v_mfma_f32_16x16x32_bf16 v[126:129], v[150:153], v[202:205], v[126:129]
	v_mfma_f32_16x16x32_bf16 v[126:129], v[168:171], v[206:209], v[126:129]
	v_mfma_f32_16x16x32_bf16 v[118:121], v[172:175], v[202:205], v[118:121]
	v_mfma_f32_16x16x32_bf16 v[118:121], v[176:179], v[206:209], v[118:121]
	v_mfma_f32_16x16x32_bf16 v[122:125], v[186:189], v[202:205], v[122:125]
	v_mfma_f32_16x16x32_bf16 v[122:125], v[190:193], v[206:209], v[122:125]
	v_mfma_f32_16x16x32_bf16 v[114:117], v[194:197], v[202:205], v[114:117]
	v_mfma_f32_16x16x32_bf16 v[114:117], v[198:201], v[206:209], v[114:117]
	v_mfma_f32_16x16x32_bf16 v[110:113], v[150:153], v[210:213], v[110:113]
	v_mfma_f32_16x16x32_bf16 v[110:113], v[168:171], v[214:217], v[110:113]
	v_mfma_f32_16x16x32_bf16 v[102:105], v[172:175], v[210:213], v[102:105]
	v_mfma_f32_16x16x32_bf16 v[102:105], v[176:179], v[214:217], v[102:105]
	v_mfma_f32_16x16x32_bf16 v[106:109], v[186:189], v[210:213], v[106:109]
	v_mfma_f32_16x16x32_bf16 v[106:109], v[190:193], v[214:217], v[106:109]
	v_mfma_f32_16x16x32_bf16 v[98:101], v[194:197], v[210:213], v[98:101]
	v_mfma_f32_16x16x32_bf16 v[98:101], v[198:201], v[214:217], v[98:101]
	v_mfma_f32_16x16x32_bf16 v[94:97], v[150:153], v[218:221], v[94:97]
	v_mfma_f32_16x16x32_bf16 v[94:97], v[168:171], v[222:225], v[94:97]
	v_mfma_f32_16x16x32_bf16 v[86:89], v[172:175], v[218:221], v[86:89]
	v_mfma_f32_16x16x32_bf16 v[86:89], v[176:179], v[222:225], v[86:89]
	v_mfma_f32_16x16x32_bf16 v[90:93], v[186:189], v[218:221], v[90:93]
	v_mfma_f32_16x16x32_bf16 v[90:93], v[190:193], v[222:225], v[90:93]
	v_mfma_f32_16x16x32_bf16 v[82:85], v[194:197], v[218:221], v[82:85]
	v_mfma_f32_16x16x32_bf16 v[82:85], v[198:201], v[222:225], v[82:85]
	v_mfma_f32_16x16x32_bf16 v[78:81], v[150:153], v[226:229], v[78:81]
	v_mfma_f32_16x16x32_bf16 v[78:81], v[168:171], v[230:233], v[78:81]
	v_mfma_f32_16x16x32_bf16 v[70:73], v[172:175], v[226:229], v[70:73]
	v_mfma_f32_16x16x32_bf16 v[70:73], v[176:179], v[230:233], v[70:73]
	v_mfma_f32_16x16x32_bf16 v[74:77], v[186:189], v[226:229], v[74:77]
	v_mfma_f32_16x16x32_bf16 v[74:77], v[190:193], v[230:233], v[74:77]
	v_mfma_f32_16x16x32_bf16 v[66:69], v[194:197], v[226:229], v[66:69]
	v_mfma_f32_16x16x32_bf16 v[66:69], v[198:201], v[230:233], v[66:69]
	s_barrier
	s_add_i32 s82, s68, s29
	s_add_u32 s98, s50, 0x80
	s_addc_u32 s99, s51, 0
	s_mov_b32 m0, s82
	ds_read_b128 v[202:205], v164 offset:16384
	ds_read_b128 v[206:209], v164 offset:17408
	ds_read_b128 v[210:213], v164 offset:18432
	ds_read_b128 v[214:217], v164 offset:19456
	ds_read_b128 v[218:221], v164 offset:20480
	ds_read_b128 v[222:225], v164 offset:21504
	ds_read_b128 v[226:229], v164 offset:22528
	ds_read_b128 v[230:233], v164 offset:23552
	global_load_lds_dwordx4 v134, s[50:51]
	s_add_i32 m0, s82, 0x2000
	s_add_u32 s82, s50, 0x100000
	s_addc_u32 s83, s51, 0
	s_add_i32 s84, s69, s29
	global_load_lds_dwordx4 v138, s[50:51]
	s_mov_b32 m0, s84
	global_load_lds_dwordx4 v134, s[82:83]
	s_add_i32 m0, s84, 0x2000
	s_nop 0
	global_load_lds_dwordx4 v138, s[82:83]
	s_add_u32 s100, s80, 0x80
	s_addc_u32 s101, s81, 0
	s_mov_b32 m0, s33
	s_nop 0
	global_load_lds_dwordx4 v132, s[80:81]
	s_mov_b32 m0, s35
	s_nop 0
	global_load_lds_dwordx4 v136, s[80:81]
	s_waitcnt vmcnt(8)
	s_waitcnt lgkmcnt(0)
	s_barrier
	v_mfma_f32_16x16x32_bf16 v[62:65], v[150:153], v[202:205], v[62:65]
	v_mfma_f32_16x16x32_bf16 v[62:65], v[168:171], v[206:209], v[62:65]
	v_mfma_f32_16x16x32_bf16 v[54:57], v[172:175], v[202:205], v[54:57]
	v_mfma_f32_16x16x32_bf16 v[54:57], v[176:179], v[206:209], v[54:57]
	v_mfma_f32_16x16x32_bf16 v[58:61], v[186:189], v[202:205], v[58:61]
	v_mfma_f32_16x16x32_bf16 v[58:61], v[190:193], v[206:209], v[58:61]
	v_mfma_f32_16x16x32_bf16 v[50:53], v[194:197], v[202:205], v[50:53]
	v_mfma_f32_16x16x32_bf16 v[50:53], v[198:201], v[206:209], v[50:53]
	v_mfma_f32_16x16x32_bf16 v[46:49], v[150:153], v[210:213], v[46:49]
	v_mfma_f32_16x16x32_bf16 v[46:49], v[168:171], v[214:217], v[46:49]
	v_mfma_f32_16x16x32_bf16 v[38:41], v[172:175], v[210:213], v[38:41]
	v_mfma_f32_16x16x32_bf16 v[38:41], v[176:179], v[214:217], v[38:41]
	v_mfma_f32_16x16x32_bf16 v[42:45], v[186:189], v[210:213], v[42:45]
	v_mfma_f32_16x16x32_bf16 v[42:45], v[190:193], v[214:217], v[42:45]
	v_mfma_f32_16x16x32_bf16 v[34:37], v[194:197], v[210:213], v[34:37]
	v_mfma_f32_16x16x32_bf16 v[34:37], v[198:201], v[214:217], v[34:37]
	v_mfma_f32_16x16x32_bf16 v[30:33], v[150:153], v[218:221], v[30:33]
	v_mfma_f32_16x16x32_bf16 v[30:33], v[168:171], v[222:225], v[30:33]
	v_mfma_f32_16x16x32_bf16 v[22:25], v[172:175], v[218:221], v[22:25]
	v_mfma_f32_16x16x32_bf16 v[22:25], v[176:179], v[222:225], v[22:25]
	v_mfma_f32_16x16x32_bf16 v[26:29], v[186:189], v[218:221], v[26:29]
	v_mfma_f32_16x16x32_bf16 v[26:29], v[190:193], v[222:225], v[26:29]
	v_mfma_f32_16x16x32_bf16 v[18:21], v[194:197], v[218:221], v[18:21]
	v_mfma_f32_16x16x32_bf16 v[18:21], v[198:201], v[222:225], v[18:21]
	v_mfma_f32_16x16x32_bf16 v[14:17], v[150:153], v[226:229], v[14:17]
	v_mfma_f32_16x16x32_bf16 v[14:17], v[168:171], v[230:233], v[14:17]
	v_mfma_f32_16x16x32_bf16 v[6:9], v[172:175], v[226:229], v[6:9]
	v_mfma_f32_16x16x32_bf16 v[6:9], v[176:179], v[230:233], v[6:9]
	v_mfma_f32_16x16x32_bf16 v[10:13], v[186:189], v[226:229], v[10:13]
	v_mfma_f32_16x16x32_bf16 v[10:13], v[190:193], v[230:233], v[10:13]
	v_mfma_f32_16x16x32_bf16 v[2:5], v[194:197], v[226:229], v[2:5]
	v_mfma_f32_16x16x32_bf16 v[2:5], v[198:201], v[230:233], v[2:5]
	s_barrier
	s_add_i32 s82, 0, 0x18000
	s_add_i32 s83, 0, 0x1c000
	ds_read_b128 v[150:153], v246
	ds_read_b128 v[168:171], v246 offset:1024
	ds_read_b128 v[172:175], v246 offset:2048
	ds_read_b128 v[176:179], v246 offset:3072
	ds_read_b128 v[186:189], v247
	ds_read_b128 v[190:193], v247 offset:1024
	ds_read_b128 v[194:197], v247 offset:2048
	ds_read_b128 v[198:201], v247 offset:3072
	s_add_u32 s80, s80, 0x100000
	s_addc_u32 s81, s81, 0
	s_mov_b32 m0, s59
	ds_read_b128 v[202:205], v164 offset:32768
	ds_read_b128 v[206:209], v164 offset:33792
	ds_read_b128 v[210:213], v164 offset:34816
	ds_read_b128 v[214:217], v164 offset:35840
	ds_read_b128 v[218:221], v164 offset:36864
	ds_read_b128 v[222:225], v164 offset:37888
	ds_read_b128 v[226:229], v164 offset:38912
	ds_read_b128 v[230:233], v164 offset:39936
	global_load_lds_dwordx4 v132, s[80:81]
	s_mov_b32 m0, s62
	s_nop 0
	global_load_lds_dwordx4 v136, s[80:81]
	s_waitcnt vmcnt(8)
	s_waitcnt lgkmcnt(0)
	s_barrier
	v_mfma_f32_16x16x32_bf16 v[126:129], v[150:153], v[202:205], v[126:129]
	v_mfma_f32_16x16x32_bf16 v[126:129], v[168:171], v[206:209], v[126:129]
	v_mfma_f32_16x16x32_bf16 v[118:121], v[172:175], v[202:205], v[118:121]
	v_mfma_f32_16x16x32_bf16 v[118:121], v[176:179], v[206:209], v[118:121]
	v_mfma_f32_16x16x32_bf16 v[122:125], v[186:189], v[202:205], v[122:125]
	v_mfma_f32_16x16x32_bf16 v[122:125], v[190:193], v[206:209], v[122:125]
	v_mfma_f32_16x16x32_bf16 v[114:117], v[194:197], v[202:205], v[114:117]
	v_mfma_f32_16x16x32_bf16 v[114:117], v[198:201], v[206:209], v[114:117]
	v_mfma_f32_16x16x32_bf16 v[110:113], v[150:153], v[210:213], v[110:113]
	v_mfma_f32_16x16x32_bf16 v[110:113], v[168:171], v[214:217], v[110:113]
	v_mfma_f32_16x16x32_bf16 v[102:105], v[172:175], v[210:213], v[102:105]
	v_mfma_f32_16x16x32_bf16 v[102:105], v[176:179], v[214:217], v[102:105]
	v_mfma_f32_16x16x32_bf16 v[106:109], v[186:189], v[210:213], v[106:109]
	v_mfma_f32_16x16x32_bf16 v[106:109], v[190:193], v[214:217], v[106:109]
	v_mfma_f32_16x16x32_bf16 v[98:101], v[194:197], v[210:213], v[98:101]
	v_mfma_f32_16x16x32_bf16 v[98:101], v[198:201], v[214:217], v[98:101]
	v_mfma_f32_16x16x32_bf16 v[94:97], v[150:153], v[218:221], v[94:97]
	v_mfma_f32_16x16x32_bf16 v[94:97], v[168:171], v[222:225], v[94:97]
	v_mfma_f32_16x16x32_bf16 v[86:89], v[172:175], v[218:221], v[86:89]
	v_mfma_f32_16x16x32_bf16 v[86:89], v[176:179], v[222:225], v[86:89]
	v_mfma_f32_16x16x32_bf16 v[90:93], v[186:189], v[218:221], v[90:93]
	v_mfma_f32_16x16x32_bf16 v[90:93], v[190:193], v[222:225], v[90:93]
	v_mfma_f32_16x16x32_bf16 v[82:85], v[194:197], v[218:221], v[82:85]
	v_mfma_f32_16x16x32_bf16 v[82:85], v[198:201], v[222:225], v[82:85]
	v_mfma_f32_16x16x32_bf16 v[78:81], v[150:153], v[226:229], v[78:81]
	v_mfma_f32_16x16x32_bf16 v[78:81], v[168:171], v[230:233], v[78:81]
	v_mfma_f32_16x16x32_bf16 v[70:73], v[172:175], v[226:229], v[70:73]
	v_mfma_f32_16x16x32_bf16 v[70:73], v[176:179], v[230:233], v[70:73]
	v_mfma_f32_16x16x32_bf16 v[74:77], v[186:189], v[226:229], v[74:77]
	v_mfma_f32_16x16x32_bf16 v[74:77], v[190:193], v[230:233], v[74:77]
	v_mfma_f32_16x16x32_bf16 v[66:69], v[194:197], v[226:229], v[66:69]
	v_mfma_f32_16x16x32_bf16 v[66:69], v[198:201], v[230:233], v[66:69]
	s_barrier
	s_add_i32 s80, s82, s29
	s_mov_b32 m0, s80
	ds_read_b128 v[202:205], v164 offset:49152
	ds_read_b128 v[206:209], v164 offset:50176
	ds_read_b128 v[210:213], v164 offset:51200
	ds_read_b128 v[214:217], v164 offset:52224
	ds_read_b128 v[218:221], v164 offset:53248
	ds_read_b128 v[222:225], v164 offset:54272
	ds_read_b128 v[226:229], v164 offset:55296
	ds_read_b128 v[230:233], v164 offset:56320
	global_load_lds_dwordx4 v134, s[98:99]
	s_add_i32 m0, s80, 0x2000
	s_add_u32 s50, s50, 0x100080
	s_addc_u32 s51, s51, 0
	s_add_i32 s80, s83, s29
	global_load_lds_dwordx4 v138, s[98:99]
	s_mov_b32 m0, s80
	s_nop 0
	global_load_lds_dwordx4 v134, s[50:51]
	s_add_i32 m0, s80, 0x2000
	s_nop 0
	global_load_lds_dwordx4 v138, s[50:51]
	s_mov_b32 m0, s65
	s_nop 0
	global_load_lds_dwordx4 v132, s[100:101]
	s_mov_b32 m0, s66
	s_nop 0
	global_load_lds_dwordx4 v136, s[100:101]
	s_waitcnt vmcnt(8)
	s_waitcnt lgkmcnt(0)
	s_barrier
	v_mfma_f32_16x16x32_bf16 v[62:65], v[150:153], v[202:205], v[62:65]
	v_mfma_f32_16x16x32_bf16 v[62:65], v[168:171], v[206:209], v[62:65]
	v_mfma_f32_16x16x32_bf16 v[54:57], v[172:175], v[202:205], v[54:57]
	v_mfma_f32_16x16x32_bf16 v[54:57], v[176:179], v[206:209], v[54:57]
	v_mfma_f32_16x16x32_bf16 v[58:61], v[186:189], v[202:205], v[58:61]
	v_mfma_f32_16x16x32_bf16 v[58:61], v[190:193], v[206:209], v[58:61]
	v_mfma_f32_16x16x32_bf16 v[50:53], v[194:197], v[202:205], v[50:53]
	v_mfma_f32_16x16x32_bf16 v[50:53], v[198:201], v[206:209], v[50:53]
	v_mfma_f32_16x16x32_bf16 v[46:49], v[150:153], v[210:213], v[46:49]
	v_mfma_f32_16x16x32_bf16 v[46:49], v[168:171], v[214:217], v[46:49]
	v_mfma_f32_16x16x32_bf16 v[38:41], v[172:175], v[210:213], v[38:41]
	v_mfma_f32_16x16x32_bf16 v[38:41], v[176:179], v[214:217], v[38:41]
	v_mfma_f32_16x16x32_bf16 v[42:45], v[186:189], v[210:213], v[42:45]
	v_mfma_f32_16x16x32_bf16 v[42:45], v[190:193], v[214:217], v[42:45]
	v_mfma_f32_16x16x32_bf16 v[34:37], v[194:197], v[210:213], v[34:37]
	v_mfma_f32_16x16x32_bf16 v[34:37], v[198:201], v[214:217], v[34:37]
	v_mfma_f32_16x16x32_bf16 v[30:33], v[150:153], v[218:221], v[30:33]
	v_mfma_f32_16x16x32_bf16 v[30:33], v[168:171], v[222:225], v[30:33]
	v_mfma_f32_16x16x32_bf16 v[22:25], v[172:175], v[218:221], v[22:25]
	v_mfma_f32_16x16x32_bf16 v[22:25], v[176:179], v[222:225], v[22:25]
	v_mfma_f32_16x16x32_bf16 v[26:29], v[186:189], v[218:221], v[26:29]
	v_mfma_f32_16x16x32_bf16 v[26:29], v[190:193], v[222:225], v[26:29]
	v_mfma_f32_16x16x32_bf16 v[18:21], v[194:197], v[218:221], v[18:21]
	v_mfma_f32_16x16x32_bf16 v[18:21], v[198:201], v[222:225], v[18:21]
	v_mfma_f32_16x16x32_bf16 v[14:17], v[150:153], v[226:229], v[14:17]
	v_mfma_f32_16x16x32_bf16 v[14:17], v[168:171], v[230:233], v[14:17]
	v_mfma_f32_16x16x32_bf16 v[6:9], v[172:175], v[226:229], v[6:9]
	v_mfma_f32_16x16x32_bf16 v[6:9], v[176:179], v[230:233], v[6:9]
	v_mfma_f32_16x16x32_bf16 v[10:13], v[186:189], v[226:229], v[10:13]
	v_mfma_f32_16x16x32_bf16 v[10:13], v[190:193], v[230:233], v[10:13]
	v_mfma_f32_16x16x32_bf16 v[2:5], v[194:197], v[226:229], v[2:5]
	v_mfma_f32_16x16x32_bf16 v[2:5], v[198:201], v[230:233], v[2:5]
	s_barrier
	s_add_i32 s79, s79, 2
	s_add_u32 s6, s6, 0x100
	s_addc_u32 s7, s7, 0
	s_add_u32 s77, s77, 0x100
	s_addc_u32 s78, s78, 0
	s_cmp_gt_u32 s79, 61
	s_cbranch_scc0 .LBB0_2212
	s_setprio 0
	s_and_b64 vcc, exec, s[40:41]
	s_cbranch_vccz .LBB0_2215
	s_barrier

.Lsprio_3:
	v_add_u32_e32 v246, 0x18000, v183
	v_add_u32_e32 v247, 0x1c000, v183
.LBB0_2340:
	ds_read_b128 v[130:133], v163
	ds_read_b128 v[134:137], v163 offset:1024
	ds_read_b128 v[138:141], v163 offset:2048
	ds_read_b128 v[142:145], v163 offset:3072
	ds_read_b128 v[146:149], v190
	ds_read_b128 v[150:153], v190 offset:1024
	ds_read_b128 v[174:177], v190 offset:2048
	ds_read_b128 v[178:181], v190 offset:3072
	s_add_u32 s42, s40, 0xffd50080
	s_addc_u32 s43, s41, -1
	s_cmpk_eq_i32 s71, 0xa8
	s_cselect_b32 s45, s1, s43
	s_cselect_b32 s44, s0, s42
	s_cselect_b32 s43, s39, s70
	s_cselect_b32 s42, s38, s12
	s_add_i32 m0, s46, 0xc000
	ds_read_b128 v[186:189], v191
	ds_read_b128 v[194:197], v191 offset:1024
	ds_read_b128 v[198:201], v191 offset:2048
	ds_read_b128 v[202:205], v191 offset:3072
	ds_read_b128 v[206:209], v191 offset:4096
	ds_read_b128 v[210:213], v191 offset:5120
	ds_read_b128 v[214:217], v191 offset:6144
	ds_read_b128 v[218:221], v191 offset:7168
	global_load_lds_dwordx4 v166, s[40:41]
	s_add_i32 m0, s46, 0xe000
	s_nop 0
	global_load_lds_dwordx4 v168, s[40:41]
	s_waitcnt vmcnt(8)
	s_waitcnt lgkmcnt(0)
	s_barrier
	v_mfma_f32_16x16x32_bf16 v[126:129], v[130:133], v[186:189], v[126:129]
	v_mfma_f32_16x16x32_bf16 v[126:129], v[134:137], v[194:197], v[126:129]
	v_mfma_f32_16x16x32_bf16 v[122:125], v[138:141], v[186:189], v[122:125]
	v_mfma_f32_16x16x32_bf16 v[122:125], v[142:145], v[194:197], v[122:125]
	v_mfma_f32_16x16x32_bf16 v[118:121], v[146:149], v[186:189], v[118:121]
	v_mfma_f32_16x16x32_bf16 v[118:121], v[150:153], v[194:197], v[118:121]
	v_mfma_f32_16x16x32_bf16 v[114:117], v[174:177], v[186:189], v[114:117]
	v_mfma_f32_16x16x32_bf16 v[114:117], v[178:181], v[194:197], v[114:117]
	v_mfma_f32_16x16x32_bf16 v[110:113], v[130:133], v[198:201], v[110:113]
	v_mfma_f32_16x16x32_bf16 v[110:113], v[134:137], v[202:205], v[110:113]
	v_mfma_f32_16x16x32_bf16 v[106:109], v[138:141], v[198:201], v[106:109]
	v_mfma_f32_16x16x32_bf16 v[106:109], v[142:145], v[202:205], v[106:109]
	v_mfma_f32_16x16x32_bf16 v[102:105], v[146:149], v[198:201], v[102:105]
	v_mfma_f32_16x16x32_bf16 v[102:105], v[150:153], v[202:205], v[102:105]
	v_mfma_f32_16x16x32_bf16 v[98:101], v[174:177], v[198:201], v[98:101]
	v_mfma_f32_16x16x32_bf16 v[98:101], v[178:181], v[202:205], v[98:101]
	v_mfma_f32_16x16x32_bf16 v[94:97], v[130:133], v[206:209], v[94:97]
	v_mfma_f32_16x16x32_bf16 v[94:97], v[134:137], v[210:213], v[94:97]
	v_mfma_f32_16x16x32_bf16 v[90:93], v[138:141], v[206:209], v[90:93]
	v_mfma_f32_16x16x32_bf16 v[90:93], v[142:145], v[210:213], v[90:93]
	v_mfma_f32_16x16x32_bf16 v[86:89], v[146:149], v[206:209], v[86:89]
	v_mfma_f32_16x16x32_bf16 v[86:89], v[150:153], v[210:213], v[86:89]
	v_mfma_f32_16x16x32_bf16 v[82:85], v[174:177], v[206:209], v[82:85]
	v_mfma_f32_16x16x32_bf16 v[82:85], v[178:181], v[210:213], v[82:85]
	v_mfma_f32_16x16x32_bf16 v[78:81], v[130:133], v[214:217], v[78:81]
	v_mfma_f32_16x16x32_bf16 v[78:81], v[134:137], v[218:221], v[78:81]
	v_mfma_f32_16x16x32_bf16 v[74:77], v[138:141], v[214:217], v[74:77]
	v_mfma_f32_16x16x32_bf16 v[74:77], v[142:145], v[218:221], v[74:77]
	v_mfma_f32_16x16x32_bf16 v[70:73], v[146:149], v[214:217], v[70:73]
	v_mfma_f32_16x16x32_bf16 v[70:73], v[150:153], v[218:221], v[70:73]
	v_mfma_f32_16x16x32_bf16 v[66:69], v[174:177], v[214:217], v[66:69]
	v_mfma_f32_16x16x32_bf16 v[66:69], v[178:181], v[218:221], v[66:69]
	s_barrier
	s_add_i32 s72, s65, s35
	s_add_u32 s98, s42, 0x80
	s_addc_u32 s99, s43, 0
	s_mov_b32 m0, s72
	ds_read_b128 v[186:189], v191 offset:16384
	ds_read_b128 v[194:197], v191 offset:17408
	ds_read_b128 v[198:201], v191 offset:18432
	ds_read_b128 v[202:205], v191 offset:19456
	ds_read_b128 v[206:209], v191 offset:20480
	ds_read_b128 v[210:213], v191 offset:21504
	ds_read_b128 v[214:217], v191 offset:22528
	ds_read_b128 v[218:221], v191 offset:23552
	global_load_lds_dwordx4 v156, s[42:43]
	s_add_i32 m0, s72, 0x2000
	s_add_u32 s72, s42, 0x2b0000
	s_addc_u32 s73, s43, 0
	s_add_i32 s74, s66, s35
	global_load_lds_dwordx4 v160, s[42:43]
	s_mov_b32 m0, s74
	global_load_lds_dwordx4 v156, s[72:73]
	s_add_i32 m0, s74, 0x2000
	s_nop 0
	global_load_lds_dwordx4 v160, s[72:73]
	s_add_u32 s100, s44, 0x80
	s_addc_u32 s101, s45, 0
	s_mov_b32 m0, s46
	s_nop 0
	global_load_lds_dwordx4 v154, s[44:45]
	s_mov_b32 m0, s47
	s_nop 0
	global_load_lds_dwordx4 v158, s[44:45]
	s_waitcnt vmcnt(8)
	s_waitcnt lgkmcnt(0)
	s_barrier
	v_mfma_f32_16x16x32_bf16 v[62:65], v[130:133], v[186:189], v[62:65]
	v_mfma_f32_16x16x32_bf16 v[62:65], v[134:137], v[194:197], v[62:65]
	v_mfma_f32_16x16x32_bf16 v[58:61], v[138:141], v[186:189], v[58:61]
	v_mfma_f32_16x16x32_bf16 v[58:61], v[142:145], v[194:197], v[58:61]
	v_mfma_f32_16x16x32_bf16 v[54:57], v[146:149], v[186:189], v[54:57]
	v_mfma_f32_16x16x32_bf16 v[54:57], v[150:153], v[194:197], v[54:57]
	v_mfma_f32_16x16x32_bf16 v[50:53], v[174:177], v[186:189], v[50:53]
	v_mfma_f32_16x16x32_bf16 v[50:53], v[178:181], v[194:197], v[50:53]
	v_mfma_f32_16x16x32_bf16 v[46:49], v[130:133], v[198:201], v[46:49]
	v_mfma_f32_16x16x32_bf16 v[46:49], v[134:137], v[202:205], v[46:49]
	v_mfma_f32_16x16x32_bf16 v[42:45], v[138:141], v[198:201], v[42:45]
	v_mfma_f32_16x16x32_bf16 v[42:45], v[142:145], v[202:205], v[42:45]
	v_mfma_f32_16x16x32_bf16 v[38:41], v[146:149], v[198:201], v[38:41]
	v_mfma_f32_16x16x32_bf16 v[38:41], v[150:153], v[202:205], v[38:41]
	v_mfma_f32_16x16x32_bf16 v[34:37], v[174:177], v[198:201], v[34:37]
	v_mfma_f32_16x16x32_bf16 v[34:37], v[178:181], v[202:205], v[34:37]
	v_mfma_f32_16x16x32_bf16 v[30:33], v[130:133], v[206:209], v[30:33]
	v_mfma_f32_16x16x32_bf16 v[30:33], v[134:137], v[210:213], v[30:33]
	v_mfma_f32_16x16x32_bf16 v[26:29], v[138:141], v[206:209], v[26:29]
	v_mfma_f32_16x16x32_bf16 v[26:29], v[142:145], v[210:213], v[26:29]
	v_mfma_f32_16x16x32_bf16 v[22:25], v[146:149], v[206:209], v[22:25]
	v_mfma_f32_16x16x32_bf16 v[22:25], v[150:153], v[210:213], v[22:25]
	v_mfma_f32_16x16x32_bf16 v[18:21], v[174:177], v[206:209], v[18:21]
	v_mfma_f32_16x16x32_bf16 v[18:21], v[178:181], v[210:213], v[18:21]
	v_mfma_f32_16x16x32_bf16 v[14:17], v[130:133], v[214:217], v[14:17]
	v_mfma_f32_16x16x32_bf16 v[14:17], v[134:137], v[218:221], v[14:17]
	v_mfma_f32_16x16x32_bf16 v[10:13], v[138:141], v[214:217], v[10:13]
	v_mfma_f32_16x16x32_bf16 v[10:13], v[142:145], v[218:221], v[10:13]
	v_mfma_f32_16x16x32_bf16 v[6:9], v[146:149], v[214:217], v[6:9]
	v_mfma_f32_16x16x32_bf16 v[6:9], v[150:153], v[218:221], v[6:9]
	v_mfma_f32_16x16x32_bf16 v[2:5], v[174:177], v[214:217], v[2:5]
	v_mfma_f32_16x16x32_bf16 v[2:5], v[178:181], v[218:221], v[2:5]
	s_barrier
	s_add_i32 s72, 0, 0x18000
	s_add_i32 s73, 0, 0x1c000
	ds_read_b128 v[130:133], v246
	ds_read_b128 v[134:137], v246 offset:1024
	ds_read_b128 v[138:141], v246 offset:2048
	ds_read_b128 v[142:145], v246 offset:3072
	ds_read_b128 v[146:149], v247
	ds_read_b128 v[150:153], v247 offset:1024
	ds_read_b128 v[174:177], v247 offset:2048
	ds_read_b128 v[178:181], v247 offset:3072
	s_add_u32 s44, s44, 0x2b0000
	s_addc_u32 s45, s45, 0
	s_mov_b32 m0, s48
	ds_read_b128 v[186:189], v191 offset:32768
	ds_read_b128 v[194:197], v191 offset:33792
	ds_read_b128 v[198:201], v191 offset:34816
	ds_read_b128 v[202:205], v191 offset:35840
	ds_read_b128 v[206:209], v191 offset:36864
	ds_read_b128 v[210:213], v191 offset:37888
	ds_read_b128 v[214:217], v191 offset:38912
	ds_read_b128 v[218:221], v191 offset:39936
	global_load_lds_dwordx4 v154, s[44:45]
	s_mov_b32 m0, s49
	s_nop 0
	global_load_lds_dwordx4 v158, s[44:45]
	s_waitcnt vmcnt(8)
	s_waitcnt lgkmcnt(0)
	s_barrier
	v_mfma_f32_16x16x32_bf16 v[126:129], v[130:133], v[186:189], v[126:129]
	v_mfma_f32_16x16x32_bf16 v[126:129], v[134:137], v[194:197], v[126:129]
	v_mfma_f32_16x16x32_bf16 v[122:125], v[138:141], v[186:189], v[122:125]
	v_mfma_f32_16x16x32_bf16 v[122:125], v[142:145], v[194:197], v[122:125]
	v_mfma_f32_16x16x32_bf16 v[118:121], v[146:149], v[186:189], v[118:121]
	v_mfma_f32_16x16x32_bf16 v[118:121], v[150:153], v[194:197], v[118:121]
	v_mfma_f32_16x16x32_bf16 v[114:117], v[174:177], v[186:189], v[114:117]
	v_mfma_f32_16x16x32_bf16 v[114:117], v[178:181], v[194:197], v[114:117]
	v_mfma_f32_16x16x32_bf16 v[110:113], v[130:133], v[198:201], v[110:113]
	v_mfma_f32_16x16x32_bf16 v[110:113], v[134:137], v[202:205], v[110:113]
	v_mfma_f32_16x16x32_bf16 v[106:109], v[138:141], v[198:201], v[106:109]
	v_mfma_f32_16x16x32_bf16 v[106:109], v[142:145], v[202:205], v[106:109]
	v_mfma_f32_16x16x32_bf16 v[102:105], v[146:149], v[198:201], v[102:105]
	v_mfma_f32_16x16x32_bf16 v[102:105], v[150:153], v[202:205], v[102:105]
	v_mfma_f32_16x16x32_bf16 v[98:101], v[174:177], v[198:201], v[98:101]
	v_mfma_f32_16x16x32_bf16 v[98:101], v[178:181], v[202:205], v[98:101]
	v_mfma_f32_16x16x32_bf16 v[94:97], v[130:133], v[206:209], v[94:97]
	v_mfma_f32_16x16x32_bf16 v[94:97], v[134:137], v[210:213], v[94:97]
	v_mfma_f32_16x16x32_bf16 v[90:93], v[138:141], v[206:209], v[90:93]
	v_mfma_f32_16x16x32_bf16 v[90:93], v[142:145], v[210:213], v[90:93]
	v_mfma_f32_16x16x32_bf16 v[86:89], v[146:149], v[206:209], v[86:89]
	v_mfma_f32_16x16x32_bf16 v[86:89], v[150:153], v[210:213], v[86:89]
	v_mfma_f32_16x16x32_bf16 v[82:85], v[174:177], v[206:209], v[82:85]
	v_mfma_f32_16x16x32_bf16 v[82:85], v[178:181], v[210:213], v[82:85]
	v_mfma_f32_16x16x32_bf16 v[78:81], v[130:133], v[214:217], v[78:81]
	v_mfma_f32_16x16x32_bf16 v[78:81], v[134:137], v[218:221], v[78:81]
	v_mfma_f32_16x16x32_bf16 v[74:77], v[138:141], v[214:217], v[74:77]
	v_mfma_f32_16x16x32_bf16 v[74:77], v[142:145], v[218:221], v[74:77]
	v_mfma_f32_16x16x32_bf16 v[70:73], v[146:149], v[214:217], v[70:73]
	v_mfma_f32_16x16x32_bf16 v[70:73], v[150:153], v[218:221], v[70:73]
	v_mfma_f32_16x16x32_bf16 v[66:69], v[174:177], v[214:217], v[66:69]
	v_mfma_f32_16x16x32_bf16 v[66:69], v[178:181], v[218:221], v[66:69]
	s_barrier
	s_add_i32 s44, s72, s35
	s_mov_b32 m0, s44
	ds_read_b128 v[186:189], v191 offset:49152
	ds_read_b128 v[194:197], v191 offset:50176
	ds_read_b128 v[198:201], v191 offset:51200
	ds_read_b128 v[202:205], v191 offset:52224
	ds_read_b128 v[206:209], v191 offset:53248
	ds_read_b128 v[210:213], v191 offset:54272
	ds_read_b128 v[214:217], v191 offset:55296
	ds_read_b128 v[218:221], v191 offset:56320
	global_load_lds_dwordx4 v156, s[98:99]
	s_add_i32 m0, s44, 0x2000
	s_add_u32 s42, s42, 0x2b0080
	s_addc_u32 s43, s43, 0
	s_add_i32 s44, s73, s35
	global_load_lds_dwordx4 v160, s[98:99]
	s_mov_b32 m0, s44
	s_nop 0
	global_load_lds_dwordx4 v156, s[42:43]
	s_add_i32 m0, s44, 0x2000
	s_nop 0
	global_load_lds_dwordx4 v160, s[42:43]
	s_mov_b32 m0, s51
	s_nop 0
	global_load_lds_dwordx4 v154, s[100:101]
	s_mov_b32 m0, s59
	s_nop 0
	global_load_lds_dwordx4 v158, s[100:101]
	s_waitcnt vmcnt(8)
	s_waitcnt lgkmcnt(0)
	s_barrier
	v_mfma_f32_16x16x32_bf16 v[62:65], v[130:133], v[186:189], v[62:65]
	v_mfma_f32_16x16x32_bf16 v[62:65], v[134:137], v[194:197], v[62:65]
	v_mfma_f32_16x16x32_bf16 v[58:61], v[138:141], v[186:189], v[58:61]
	v_mfma_f32_16x16x32_bf16 v[58:61], v[142:145], v[194:197], v[58:61]
	v_mfma_f32_16x16x32_bf16 v[54:57], v[146:149], v[186:189], v[54:57]
	v_mfma_f32_16x16x32_bf16 v[54:57], v[150:153], v[194:197], v[54:57]
	v_mfma_f32_16x16x32_bf16 v[50:53], v[174:177], v[186:189], v[50:53]
	v_mfma_f32_16x16x32_bf16 v[50:53], v[178:181], v[194:197], v[50:53]
	v_mfma_f32_16x16x32_bf16 v[46:49], v[130:133], v[198:201], v[46:49]
	v_mfma_f32_16x16x32_bf16 v[46:49], v[134:137], v[202:205], v[46:49]
	v_mfma_f32_16x16x32_bf16 v[42:45], v[138:141], v[198:201], v[42:45]
	v_mfma_f32_16x16x32_bf16 v[42:45], v[142:145], v[202:205], v[42:45]
	v_mfma_f32_16x16x32_bf16 v[38:41], v[146:149], v[198:201], v[38:41]
	v_mfma_f32_16x16x32_bf16 v[38:41], v[150:153], v[202:205], v[38:41]
	v_mfma_f32_16x16x32_bf16 v[34:37], v[174:177], v[198:201], v[34:37]
	v_mfma_f32_16x16x32_bf16 v[34:37], v[178:181], v[202:205], v[34:37]
	v_mfma_f32_16x16x32_bf16 v[30:33], v[130:133], v[206:209], v[30:33]
	v_mfma_f32_16x16x32_bf16 v[30:33], v[134:137], v[210:213], v[30:33]
	v_mfma_f32_16x16x32_bf16 v[26:29], v[138:141], v[206:209], v[26:29]
	v_mfma_f32_16x16x32_bf16 v[26:29], v[142:145], v[210:213], v[26:29]
	v_mfma_f32_16x16x32_bf16 v[22:25], v[146:149], v[206:209], v[22:25]
	v_mfma_f32_16x16x32_bf16 v[22:25], v[150:153], v[210:213], v[22:25]
	v_mfma_f32_16x16x32_bf16 v[18:21], v[174:177], v[206:209], v[18:21]
	v_mfma_f32_16x16x32_bf16 v[18:21], v[178:181], v[210:213], v[18:21]
	v_mfma_f32_16x16x32_bf16 v[14:17], v[130:133], v[214:217], v[14:17]
	v_mfma_f32_16x16x32_bf16 v[14:17], v[134:137], v[218:221], v[14:17]
	v_mfma_f32_16x16x32_bf16 v[10:13], v[138:141], v[214:217], v[10:13]
	v_mfma_f32_16x16x32_bf16 v[10:13], v[142:145], v[218:221], v[10:13]
	v_mfma_f32_16x16x32_bf16 v[6:9], v[146:149], v[214:217], v[6:9]
	v_mfma_f32_16x16x32_bf16 v[6:9], v[150:153], v[218:221], v[6:9]
	v_mfma_f32_16x16x32_bf16 v[2:5], v[174:177], v[214:217], v[2:5]
	v_mfma_f32_16x16x32_bf16 v[2:5], v[178:181], v[218:221], v[2:5]
	s_barrier
	s_add_i32 s71, s71, 2
	s_add_u32 s40, s40, 0x100
	s_addc_u32 s41, s41, 0
	s_add_u32 s12, s12, 0x100
	s_addc_u32 s70, s70, 0
	s_cmpk_gt_u32 s71, 0xa9
	s_cbranch_scc0 .LBB0_2340
	s_setprio 0
	s_and_b64 vcc, exec, s[36:37]
	s_cbranch_vccz .LBB0_2343
	s_barrier

.Lsprio_4:
	v_add_u32_e32 v246, 0x18000, v163
	v_add_u32_e32 v247, 0x1c000, v163
.LBB0_2464:
	ds_read_b128 v[150:153], v167
	ds_read_b128 v[172:175], v167 offset:1024
	ds_read_b128 v[176:179], v167 offset:2048
	ds_read_b128 v[184:187], v167 offset:3072
	ds_read_b128 v[188:191], v168
	ds_read_b128 v[192:195], v168 offset:1024
	ds_read_b128 v[196:199], v168 offset:2048
	ds_read_b128 v[200:203], v168 offset:3072
	s_add_u32 s74, s6, 0xfff00080
	s_addc_u32 s75, s7, -1
	s_cmp_eq_u32 s87, 60
	s_cselect_b32 s77, s47, s75
	s_cselect_b32 s76, s83, s74
	s_cselect_b32 s75, s45, s86
	s_cselect_b32 s74, s84, s85
	s_add_i32 m0, s59, 0xc000
	ds_read_b128 v[204:207], v169
	ds_read_b128 v[208:211], v169 offset:1024
	ds_read_b128 v[212:215], v169 offset:2048
	ds_read_b128 v[216:219], v169 offset:3072
	ds_read_b128 v[220:223], v169 offset:4096
	ds_read_b128 v[224:227], v169 offset:5120
	ds_read_b128 v[228:231], v169 offset:6144
	ds_read_b128 v[232:235], v169 offset:7168
	global_load_lds_dwordx4 v142, s[6:7]
	s_add_i32 m0, s59, 0xe000
	s_nop 0
	global_load_lds_dwordx4 v144, s[6:7]
	s_waitcnt vmcnt(8)
	s_waitcnt lgkmcnt(0)
	s_barrier
	v_mfma_f32_16x16x32_bf16 v[126:129], v[150:153], v[204:207], v[126:129]
	v_mfma_f32_16x16x32_bf16 v[126:129], v[172:175], v[208:211], v[126:129]
	v_mfma_f32_16x16x32_bf16 v[122:125], v[176:179], v[204:207], v[122:125]
	v_mfma_f32_16x16x32_bf16 v[122:125], v[184:187], v[208:211], v[122:125]
	v_mfma_f32_16x16x32_bf16 v[118:121], v[188:191], v[204:207], v[118:121]
	v_mfma_f32_16x16x32_bf16 v[118:121], v[192:195], v[208:211], v[118:121]
	v_mfma_f32_16x16x32_bf16 v[114:117], v[196:199], v[204:207], v[114:117]
	v_mfma_f32_16x16x32_bf16 v[114:117], v[200:203], v[208:211], v[114:117]
	v_mfma_f32_16x16x32_bf16 v[110:113], v[150:153], v[212:215], v[110:113]
	v_mfma_f32_16x16x32_bf16 v[110:113], v[172:175], v[216:219], v[110:113]
	v_mfma_f32_16x16x32_bf16 v[106:109], v[176:179], v[212:215], v[106:109]
	v_mfma_f32_16x16x32_bf16 v[106:109], v[184:187], v[216:219], v[106:109]
	v_mfma_f32_16x16x32_bf16 v[102:105], v[188:191], v[212:215], v[102:105]
	v_mfma_f32_16x16x32_bf16 v[102:105], v[192:195], v[216:219], v[102:105]
	v_mfma_f32_16x16x32_bf16 v[98:101], v[196:199], v[212:215], v[98:101]
	v_mfma_f32_16x16x32_bf16 v[98:101], v[200:203], v[216:219], v[98:101]
	v_mfma_f32_16x16x32_bf16 v[94:97], v[150:153], v[220:223], v[94:97]
	v_mfma_f32_16x16x32_bf16 v[94:97], v[172:175], v[224:227], v[94:97]
	v_mfma_f32_16x16x32_bf16 v[90:93], v[176:179], v[220:223], v[90:93]
	v_mfma_f32_16x16x32_bf16 v[90:93], v[184:187], v[224:227], v[90:93]
	v_mfma_f32_16x16x32_bf16 v[86:89], v[188:191], v[220:223], v[86:89]
	v_mfma_f32_16x16x32_bf16 v[86:89], v[192:195], v[224:227], v[86:89]
	v_mfma_f32_16x16x32_bf16 v[82:85], v[196:199], v[220:223], v[82:85]
	v_mfma_f32_16x16x32_bf16 v[82:85], v[200:203], v[224:227], v[82:85]
	v_mfma_f32_16x16x32_bf16 v[78:81], v[150:153], v[228:231], v[78:81]
	v_mfma_f32_16x16x32_bf16 v[78:81], v[172:175], v[232:235], v[78:81]
	v_mfma_f32_16x16x32_bf16 v[74:77], v[176:179], v[228:231], v[74:77]
	v_mfma_f32_16x16x32_bf16 v[74:77], v[184:187], v[232:235], v[74:77]
	v_mfma_f32_16x16x32_bf16 v[70:73], v[188:191], v[228:231], v[70:73]
	v_mfma_f32_16x16x32_bf16 v[70:73], v[192:195], v[232:235], v[70:73]
	v_mfma_f32_16x16x32_bf16 v[66:69], v[196:199], v[228:231], v[66:69]
	v_mfma_f32_16x16x32_bf16 v[66:69], v[200:203], v[232:235], v[66:69]
	s_barrier
	s_add_i32 s88, s70, s27
	s_add_u32 s98, s74, 0x80
	s_addc_u32 s99, s75, 0
	s_mov_b32 m0, s88
	ds_read_b128 v[204:207], v169 offset:16384
	ds_read_b128 v[208:211], v169 offset:17408
	ds_read_b128 v[212:215], v169 offset:18432
	ds_read_b128 v[216:219], v169 offset:19456
	ds_read_b128 v[220:223], v169 offset:20480
	ds_read_b128 v[224:227], v169 offset:21504
	ds_read_b128 v[228:231], v169 offset:22528
	ds_read_b128 v[232:235], v169 offset:23552
	global_load_lds_dwordx4 v132, s[74:75]
	s_add_i32 m0, s88, 0x2000
	s_add_u32 s88, s74, 0x100000
	s_addc_u32 s89, s75, 0
	s_add_i32 s90, s71, s27
	global_load_lds_dwordx4 v136, s[74:75]
	s_mov_b32 m0, s90
	global_load_lds_dwordx4 v132, s[88:89]
	s_add_i32 m0, s90, 0x2000
	s_nop 0
	global_load_lds_dwordx4 v136, s[88:89]
	s_add_u32 s100, s76, 0x80
	s_addc_u32 s101, s77, 0
	s_mov_b32 m0, s59
	s_nop 0
	global_load_lds_dwordx4 v130, s[76:77]
	s_mov_b32 m0, s62
	s_nop 0
	global_load_lds_dwordx4 v134, s[76:77]
	s_waitcnt vmcnt(8)
	s_waitcnt lgkmcnt(0)
	s_barrier
	v_mfma_f32_16x16x32_bf16 v[62:65], v[150:153], v[204:207], v[62:65]
	v_mfma_f32_16x16x32_bf16 v[62:65], v[172:175], v[208:211], v[62:65]
	v_mfma_f32_16x16x32_bf16 v[58:61], v[176:179], v[204:207], v[58:61]
	v_mfma_f32_16x16x32_bf16 v[58:61], v[184:187], v[208:211], v[58:61]
	v_mfma_f32_16x16x32_bf16 v[54:57], v[188:191], v[204:207], v[54:57]
	v_mfma_f32_16x16x32_bf16 v[54:57], v[192:195], v[208:211], v[54:57]
	v_mfma_f32_16x16x32_bf16 v[46:49], v[196:199], v[204:207], v[46:49]
	v_mfma_f32_16x16x32_bf16 v[46:49], v[200:203], v[208:211], v[46:49]
	v_mfma_f32_16x16x32_bf16 v[50:53], v[150:153], v[212:215], v[50:53]
	v_mfma_f32_16x16x32_bf16 v[50:53], v[172:175], v[216:219], v[50:53]
	v_mfma_f32_16x16x32_bf16 v[42:45], v[176:179], v[212:215], v[42:45]
	v_mfma_f32_16x16x32_bf16 v[42:45], v[184:187], v[216:219], v[42:45]
	v_mfma_f32_16x16x32_bf16 v[38:41], v[188:191], v[212:215], v[38:41]
	v_mfma_f32_16x16x32_bf16 v[38:41], v[192:195], v[216:219], v[38:41]
	v_mfma_f32_16x16x32_bf16 v[30:33], v[196:199], v[212:215], v[30:33]
	v_mfma_f32_16x16x32_bf16 v[30:33], v[200:203], v[216:219], v[30:33]
	v_mfma_f32_16x16x32_bf16 v[34:37], v[150:153], v[220:223], v[34:37]
	v_mfma_f32_16x16x32_bf16 v[34:37], v[172:175], v[224:227], v[34:37]
	v_mfma_f32_16x16x32_bf16 v[26:29], v[176:179], v[220:223], v[26:29]
	v_mfma_f32_16x16x32_bf16 v[26:29], v[184:187], v[224:227], v[26:29]
	v_mfma_f32_16x16x32_bf16 v[22:25], v[188:191], v[220:223], v[22:25]
	v_mfma_f32_16x16x32_bf16 v[22:25], v[192:195], v[224:227], v[22:25]
	v_mfma_f32_16x16x32_bf16 v[14:17], v[196:199], v[220:223], v[14:17]
	v_mfma_f32_16x16x32_bf16 v[14:17], v[200:203], v[224:227], v[14:17]
	v_mfma_f32_16x16x32_bf16 v[18:21], v[150:153], v[228:231], v[18:21]
	v_mfma_f32_16x16x32_bf16 v[18:21], v[172:175], v[232:235], v[18:21]
	v_mfma_f32_16x16x32_bf16 v[10:13], v[176:179], v[228:231], v[10:13]
	v_mfma_f32_16x16x32_bf16 v[10:13], v[184:187], v[232:235], v[10:13]
	v_mfma_f32_16x16x32_bf16 v[6:9], v[188:191], v[228:231], v[6:9]
	v_mfma_f32_16x16x32_bf16 v[6:9], v[192:195], v[232:235], v[6:9]
	v_mfma_f32_16x16x32_bf16 v[2:5], v[196:199], v[228:231], v[2:5]
	v_mfma_f32_16x16x32_bf16 v[2:5], v[200:203], v[232:235], v[2:5]
	s_barrier
	s_add_i32 s88, 0, 0x18000
	s_add_i32 s89, 0, 0x1c000
	ds_read_b128 v[150:153], v246
	ds_read_b128 v[172:175], v246 offset:1024
	ds_read_b128 v[176:179], v246 offset:2048
	ds_read_b128 v[184:187], v246 offset:3072
	ds_read_b128 v[188:191], v247
	ds_read_b128 v[192:195], v247 offset:1024
	ds_read_b128 v[196:199], v247 offset:2048
	ds_read_b128 v[200:203], v247 offset:3072
	s_add_u32 s76, s76, 0x100000
	s_addc_u32 s77, s77, 0
	s_mov_b32 m0, s63
	ds_read_b128 v[204:207], v169 offset:32768
	ds_read_b128 v[208:211], v169 offset:33792
	ds_read_b128 v[212:215], v169 offset:34816
	ds_read_b128 v[216:219], v169 offset:35840
	ds_read_b128 v[220:223], v169 offset:36864
	ds_read_b128 v[224:227], v169 offset:37888
	ds_read_b128 v[228:231], v169 offset:38912
	ds_read_b128 v[232:235], v169 offset:39936
	global_load_lds_dwordx4 v130, s[76:77]
	s_mov_b32 m0, s65
	s_nop 0
	global_load_lds_dwordx4 v134, s[76:77]
	s_waitcnt vmcnt(8)
	s_waitcnt lgkmcnt(0)
	s_barrier
	v_mfma_f32_16x16x32_bf16 v[126:129], v[150:153], v[204:207], v[126:129]
	v_mfma_f32_16x16x32_bf16 v[126:129], v[172:175], v[208:211], v[126:129]
	v_mfma_f32_16x16x32_bf16 v[122:125], v[176:179], v[204:207], v[122:125]
	v_mfma_f32_16x16x32_bf16 v[122:125], v[184:187], v[208:211], v[122:125]
	v_mfma_f32_16x16x32_bf16 v[118:121], v[188:191], v[204:207], v[118:121]
	v_mfma_f32_16x16x32_bf16 v[118:121], v[192:195], v[208:211], v[118:121]
	v_mfma_f32_16x16x32_bf16 v[114:117], v[196:199], v[204:207], v[114:117]
	v_mfma_f32_16x16x32_bf16 v[114:117], v[200:203], v[208:211], v[114:117]
	v_mfma_f32_16x16x32_bf16 v[110:113], v[150:153], v[212:215], v[110:113]
	v_mfma_f32_16x16x32_bf16 v[110:113], v[172:175], v[216:219], v[110:113]
	v_mfma_f32_16x16x32_bf16 v[106:109], v[176:179], v[212:215], v[106:109]
	v_mfma_f32_16x16x32_bf16 v[106:109], v[184:187], v[216:219], v[106:109]
	v_mfma_f32_16x16x32_bf16 v[102:105], v[188:191], v[212:215], v[102:105]
	v_mfma_f32_16x16x32_bf16 v[102:105], v[192:195], v[216:219], v[102:105]
	v_mfma_f32_16x16x32_bf16 v[98:101], v[196:199], v[212:215], v[98:101]
	v_mfma_f32_16x16x32_bf16 v[98:101], v[200:203], v[216:219], v[98:101]
	v_mfma_f32_16x16x32_bf16 v[94:97], v[150:153], v[220:223], v[94:97]
	v_mfma_f32_16x16x32_bf16 v[94:97], v[172:175], v[224:227], v[94:97]
	v_mfma_f32_16x16x32_bf16 v[90:93], v[176:179], v[220:223], v[90:93]
	v_mfma_f32_16x16x32_bf16 v[90:93], v[184:187], v[224:227], v[90:93]
	v_mfma_f32_16x16x32_bf16 v[86:89], v[188:191], v[220:223], v[86:89]
	v_mfma_f32_16x16x32_bf16 v[86:89], v[192:195], v[224:227], v[86:89]
	v_mfma_f32_16x16x32_bf16 v[82:85], v[196:199], v[220:223], v[82:85]
	v_mfma_f32_16x16x32_bf16 v[82:85], v[200:203], v[224:227], v[82:85]
	v_mfma_f32_16x16x32_bf16 v[78:81], v[150:153], v[228:231], v[78:81]
	v_mfma_f32_16x16x32_bf16 v[78:81], v[172:175], v[232:235], v[78:81]
	v_mfma_f32_16x16x32_bf16 v[74:77], v[176:179], v[228:231], v[74:77]
	v_mfma_f32_16x16x32_bf16 v[74:77], v[184:187], v[232:235], v[74:77]
	v_mfma_f32_16x16x32_bf16 v[70:73], v[188:191], v[228:231], v[70:73]
	v_mfma_f32_16x16x32_bf16 v[70:73], v[192:195], v[232:235], v[70:73]
	v_mfma_f32_16x16x32_bf16 v[66:69], v[196:199], v[228:231], v[66:69]
	v_mfma_f32_16x16x32_bf16 v[66:69], v[200:203], v[232:235], v[66:69]
	s_barrier
	s_add_i32 s76, s88, s27
	s_mov_b32 m0, s76
	ds_read_b128 v[204:207], v169 offset:49152
	ds_read_b128 v[208:211], v169 offset:50176
	ds_read_b128 v[212:215], v169 offset:51200
	ds_read_b128 v[216:219], v169 offset:52224
	ds_read_b128 v[220:223], v169 offset:53248
	ds_read_b128 v[224:227], v169 offset:54272
	ds_read_b128 v[228:231], v169 offset:55296
	ds_read_b128 v[232:235], v169 offset:56320
	global_load_lds_dwordx4 v132, s[98:99]
	s_add_i32 m0, s76, 0x2000
	s_add_u32 s74, s74, 0x100080
	s_addc_u32 s75, s75, 0
	s_add_i32 s76, s89, s27
	global_load_lds_dwordx4 v136, s[98:99]
	s_mov_b32 m0, s76
	s_nop 0
	global_load_lds_dwordx4 v132, s[74:75]
	s_add_i32 m0, s76, 0x2000
	s_nop 0
	global_load_lds_dwordx4 v136, s[74:75]
	s_mov_b32 m0, s67
	s_nop 0
	global_load_lds_dwordx4 v130, s[100:101]
	s_mov_b32 m0, s68
	s_nop 0
	global_load_lds_dwordx4 v134, s[100:101]
	s_waitcnt vmcnt(8)
	s_waitcnt lgkmcnt(0)
	s_barrier
	v_mfma_f32_16x16x32_bf16 v[62:65], v[150:153], v[204:207], v[62:65]
	v_mfma_f32_16x16x32_bf16 v[62:65], v[172:175], v[208:211], v[62:65]
	v_mfma_f32_16x16x32_bf16 v[58:61], v[176:179], v[204:207], v[58:61]
	v_mfma_f32_16x16x32_bf16 v[58:61], v[184:187], v[208:211], v[58:61]
	v_mfma_f32_16x16x32_bf16 v[54:57], v[188:191], v[204:207], v[54:57]
	v_mfma_f32_16x16x32_bf16 v[54:57], v[192:195], v[208:211], v[54:57]
	v_mfma_f32_16x16x32_bf16 v[46:49], v[196:199], v[204:207], v[46:49]
	v_mfma_f32_16x16x32_bf16 v[46:49], v[200:203], v[208:211], v[46:49]
	v_mfma_f32_16x16x32_bf16 v[50:53], v[150:153], v[212:215], v[50:53]
	v_mfma_f32_16x16x32_bf16 v[50:53], v[172:175], v[216:219], v[50:53]
	v_mfma_f32_16x16x32_bf16 v[42:45], v[176:179], v[212:215], v[42:45]
	v_mfma_f32_16x16x32_bf16 v[42:45], v[184:187], v[216:219], v[42:45]
	v_mfma_f32_16x16x32_bf16 v[38:41], v[188:191], v[212:215], v[38:41]
	v_mfma_f32_16x16x32_bf16 v[38:41], v[192:195], v[216:219], v[38:41]
	v_mfma_f32_16x16x32_bf16 v[30:33], v[196:199], v[212:215], v[30:33]
	v_mfma_f32_16x16x32_bf16 v[30:33], v[200:203], v[216:219], v[30:33]
	v_mfma_f32_16x16x32_bf16 v[34:37], v[150:153], v[220:223], v[34:37]
	v_mfma_f32_16x16x32_bf16 v[34:37], v[172:175], v[224:227], v[34:37]
	v_mfma_f32_16x16x32_bf16 v[26:29], v[176:179], v[220:223], v[26:29]
	v_mfma_f32_16x16x32_bf16 v[26:29], v[184:187], v[224:227], v[26:29]
	v_mfma_f32_16x16x32_bf16 v[22:25], v[188:191], v[220:223], v[22:25]
	v_mfma_f32_16x16x32_bf16 v[22:25], v[192:195], v[224:227], v[22:25]
	v_mfma_f32_16x16x32_bf16 v[14:17], v[196:199], v[220:223], v[14:17]
	v_mfma_f32_16x16x32_bf16 v[14:17], v[200:203], v[224:227], v[14:17]
	v_mfma_f32_16x16x32_bf16 v[18:21], v[150:153], v[228:231], v[18:21]
	v_mfma_f32_16x16x32_bf16 v[18:21], v[172:175], v[232:235], v[18:21]
	v_mfma_f32_16x16x32_bf16 v[10:13], v[176:179], v[228:231], v[10:13]
	v_mfma_f32_16x16x32_bf16 v[10:13], v[184:187], v[232:235], v[10:13]
	v_mfma_f32_16x16x32_bf16 v[6:9], v[188:191], v[228:231], v[6:9]
	v_mfma_f32_16x16x32_bf16 v[6:9], v[192:195], v[232:235], v[6:9]
	v_mfma_f32_16x16x32_bf16 v[2:5], v[196:199], v[228:231], v[2:5]
	v_mfma_f32_16x16x32_bf16 v[2:5], v[200:203], v[232:235], v[2:5]
	s_barrier
	s_add_i32 s87, s87, 2
	s_add_u32 s6, s6, 0x100
	s_addc_u32 s7, s7, 0
	s_add_u32 s85, s85, 0x100
	s_addc_u32 s86, s86, 0
	s_cmp_gt_u32 s87, 61
	s_cbranch_scc0 .LBB0_2464
	s_setprio 0
	s_and_b64 vcc, exec, s[38:39]
	s_cbranch_vccz .LBB0_2467
	s_barrier

.Lsprio_5:
	v_add_u32_e32 v246, 0x18000, v151
	v_add_u32_e32 v247, 0x1c000, v151
.LBB0_2494:
	ds_read_b128 v[160:163], v155
	ds_read_b128 v[164:167], v155 offset:1024
	ds_read_b128 v[168:171], v155 offset:2048
	ds_read_b128 v[172:175], v155 offset:3072
	ds_read_b128 v[176:179], v156
	ds_read_b128 v[184:187], v156 offset:1024
	ds_read_b128 v[188:191], v156 offset:2048
	ds_read_b128 v[192:195], v156 offset:3072
	s_add_u32 s48, s6, 0xfff00080
	s_addc_u32 s49, s7, -1
	s_cmp_eq_u32 s89, 60
	s_cselect_b32 s51, s43, s49
	s_cselect_b32 s50, s85, s48
	s_cselect_b32 s49, s41, s88
	s_cselect_b32 s48, s86, s87
	s_add_i32 m0, s63, 0xc000
	ds_read_b128 v[196:199], v157
	ds_read_b128 v[200:203], v157 offset:1024
	ds_read_b128 v[204:207], v157 offset:2048
	ds_read_b128 v[208:211], v157 offset:3072
	ds_read_b128 v[212:215], v157 offset:4096
	ds_read_b128 v[216:219], v157 offset:5120
	ds_read_b128 v[220:223], v157 offset:6144
	ds_read_b128 v[224:227], v157 offset:7168
	global_load_lds_dwordx4 v140, s[6:7]
	s_add_i32 m0, s63, 0xe000
	s_nop 0
	global_load_lds_dwordx4 v142, s[6:7]
	s_waitcnt vmcnt(8)
	s_waitcnt lgkmcnt(0)
	s_barrier
	v_mfma_f32_16x16x32_bf16 v[126:129], v[160:163], v[196:199], v[126:129]
	v_mfma_f32_16x16x32_bf16 v[126:129], v[164:167], v[200:203], v[126:129]
	v_mfma_f32_16x16x32_bf16 v[122:125], v[168:171], v[196:199], v[122:125]
	v_mfma_f32_16x16x32_bf16 v[122:125], v[172:175], v[200:203], v[122:125]
	v_mfma_f32_16x16x32_bf16 v[118:121], v[176:179], v[196:199], v[118:121]
	v_mfma_f32_16x16x32_bf16 v[118:121], v[184:187], v[200:203], v[118:121]
	v_mfma_f32_16x16x32_bf16 v[114:117], v[188:191], v[196:199], v[114:117]
	v_mfma_f32_16x16x32_bf16 v[114:117], v[192:195], v[200:203], v[114:117]
	v_mfma_f32_16x16x32_bf16 v[110:113], v[160:163], v[204:207], v[110:113]
	v_mfma_f32_16x16x32_bf16 v[110:113], v[164:167], v[208:211], v[110:113]
	v_mfma_f32_16x16x32_bf16 v[106:109], v[168:171], v[204:207], v[106:109]
	v_mfma_f32_16x16x32_bf16 v[106:109], v[172:175], v[208:211], v[106:109]
	v_mfma_f32_16x16x32_bf16 v[102:105], v[176:179], v[204:207], v[102:105]
	v_mfma_f32_16x16x32_bf16 v[102:105], v[184:187], v[208:211], v[102:105]
	v_mfma_f32_16x16x32_bf16 v[98:101], v[188:191], v[204:207], v[98:101]
	v_mfma_f32_16x16x32_bf16 v[98:101], v[192:195], v[208:211], v[98:101]
	v_mfma_f32_16x16x32_bf16 v[94:97], v[160:163], v[212:215], v[94:97]
	v_mfma_f32_16x16x32_bf16 v[94:97], v[164:167], v[216:219], v[94:97]
	v_mfma_f32_16x16x32_bf16 v[90:93], v[168:171], v[212:215], v[90:93]
	v_mfma_f32_16x16x32_bf16 v[90:93], v[172:175], v[216:219], v[90:93]
	v_mfma_f32_16x16x32_bf16 v[86:89], v[176:179], v[212:215], v[86:89]
	v_mfma_f32_16x16x32_bf16 v[86:89], v[184:187], v[216:219], v[86:89]
	v_mfma_f32_16x16x32_bf16 v[82:85], v[188:191], v[212:215], v[82:85]
	v_mfma_f32_16x16x32_bf16 v[82:85], v[192:195], v[216:219], v[82:85]
	v_mfma_f32_16x16x32_bf16 v[78:81], v[160:163], v[220:223], v[78:81]
	v_mfma_f32_16x16x32_bf16 v[78:81], v[164:167], v[224:227], v[78:81]
	v_mfma_f32_16x16x32_bf16 v[74:77], v[168:171], v[220:223], v[74:77]
	v_mfma_f32_16x16x32_bf16 v[74:77], v[172:175], v[224:227], v[74:77]
	v_mfma_f32_16x16x32_bf16 v[70:73], v[176:179], v[220:223], v[70:73]
	v_mfma_f32_16x16x32_bf16 v[70:73], v[184:187], v[224:227], v[70:73]
	v_mfma_f32_16x16x32_bf16 v[66:69], v[188:191], v[220:223], v[66:69]
	v_mfma_f32_16x16x32_bf16 v[66:69], v[192:195], v[224:227], v[66:69]
	s_barrier
	s_add_i32 s90, s73, s27
	s_add_u32 s98, s48, 0x80
	s_addc_u32 s99, s49, 0
	s_mov_b32 m0, s90
	ds_read_b128 v[196:199], v157 offset:16384
	ds_read_b128 v[200:203], v157 offset:17408
	ds_read_b128 v[204:207], v157 offset:18432
	ds_read_b128 v[208:211], v157 offset:19456
	ds_read_b128 v[212:215], v157 offset:20480
	ds_read_b128 v[216:219], v157 offset:21504
	ds_read_b128 v[220:223], v157 offset:22528
	ds_read_b128 v[224:227], v157 offset:23552
	global_load_lds_dwordx4 v132, s[48:49]
	s_add_i32 m0, s90, 0x2000
	s_add_u32 s90, s48, 0x100000
	s_addc_u32 s91, s49, 0
	s_add_i32 s92, s74, s27
	global_load_lds_dwordx4 v136, s[48:49]
	s_mov_b32 m0, s92
	global_load_lds_dwordx4 v132, s[90:91]
	s_add_i32 m0, s92, 0x2000
	s_nop 0
	global_load_lds_dwordx4 v136, s[90:91]
	s_add_u32 s100, s50, 0x80
	s_addc_u32 s101, s51, 0
	s_mov_b32 m0, s63
	s_nop 0
	global_load_lds_dwordx4 v130, s[50:51]
	s_mov_b32 m0, s65
	s_nop 0
	global_load_lds_dwordx4 v134, s[50:51]
	s_waitcnt vmcnt(8)
	s_waitcnt lgkmcnt(0)
	s_barrier
	v_mfma_f32_16x16x32_bf16 v[62:65], v[160:163], v[196:199], v[62:65]
	v_mfma_f32_16x16x32_bf16 v[62:65], v[164:167], v[200:203], v[62:65]
	v_mfma_f32_16x16x32_bf16 v[58:61], v[168:171], v[196:199], v[58:61]
	v_mfma_f32_16x16x32_bf16 v[58:61], v[172:175], v[200:203], v[58:61]
	v_mfma_f32_16x16x32_bf16 v[54:57], v[176:179], v[196:199], v[54:57]
	v_mfma_f32_16x16x32_bf16 v[54:57], v[184:187], v[200:203], v[54:57]
	v_mfma_f32_16x16x32_bf16 v[46:49], v[188:191], v[196:199], v[46:49]
	v_mfma_f32_16x16x32_bf16 v[46:49], v[192:195], v[200:203], v[46:49]
	v_mfma_f32_16x16x32_bf16 v[50:53], v[160:163], v[204:207], v[50:53]
	v_mfma_f32_16x16x32_bf16 v[50:53], v[164:167], v[208:211], v[50:53]
	v_mfma_f32_16x16x32_bf16 v[42:45], v[168:171], v[204:207], v[42:45]
	v_mfma_f32_16x16x32_bf16 v[42:45], v[172:175], v[208:211], v[42:45]
	v_mfma_f32_16x16x32_bf16 v[38:41], v[176:179], v[204:207], v[38:41]
	v_mfma_f32_16x16x32_bf16 v[38:41], v[184:187], v[208:211], v[38:41]
	v_mfma_f32_16x16x32_bf16 v[30:33], v[188:191], v[204:207], v[30:33]
	v_mfma_f32_16x16x32_bf16 v[30:33], v[192:195], v[208:211], v[30:33]
	v_mfma_f32_16x16x32_bf16 v[34:37], v[160:163], v[212:215], v[34:37]
	v_mfma_f32_16x16x32_bf16 v[34:37], v[164:167], v[216:219], v[34:37]
	v_mfma_f32_16x16x32_bf16 v[26:29], v[168:171], v[212:215], v[26:29]
	v_mfma_f32_16x16x32_bf16 v[26:29], v[172:175], v[216:219], v[26:29]
	v_mfma_f32_16x16x32_bf16 v[22:25], v[176:179], v[212:215], v[22:25]
	v_mfma_f32_16x16x32_bf16 v[22:25], v[184:187], v[216:219], v[22:25]
	v_mfma_f32_16x16x32_bf16 v[14:17], v[188:191], v[212:215], v[14:17]
	v_mfma_f32_16x16x32_bf16 v[14:17], v[192:195], v[216:219], v[14:17]
	v_mfma_f32_16x16x32_bf16 v[18:21], v[160:163], v[220:223], v[18:21]
	v_mfma_f32_16x16x32_bf16 v[18:21], v[164:167], v[224:227], v[18:21]
	v_mfma_f32_16x16x32_bf16 v[10:13], v[168:171], v[220:223], v[10:13]
	v_mfma_f32_16x16x32_bf16 v[10:13], v[172:175], v[224:227], v[10:13]
	v_mfma_f32_16x16x32_bf16 v[6:9], v[176:179], v[220:223], v[6:9]
	v_mfma_f32_16x16x32_bf16 v[6:9], v[184:187], v[224:227], v[6:9]
	v_mfma_f32_16x16x32_bf16 v[2:5], v[188:191], v[220:223], v[2:5]
	v_mfma_f32_16x16x32_bf16 v[2:5], v[192:195], v[224:227], v[2:5]
	s_barrier
	s_add_i32 s90, 0, 0x18000
	s_add_i32 s91, 0, 0x1c000
	ds_read_b128 v[160:163], v246
	ds_read_b128 v[164:167], v246 offset:1024
	ds_read_b128 v[168:171], v246 offset:2048
	ds_read_b128 v[172:175], v246 offset:3072
	ds_read_b128 v[176:179], v247
	ds_read_b128 v[184:187], v247 offset:1024
	ds_read_b128 v[188:191], v247 offset:2048
	ds_read_b128 v[192:195], v247 offset:3072
	s_add_u32 s50, s50, 0x100000
	s_addc_u32 s51, s51, 0
	s_mov_b32 m0, s66
	ds_read_b128 v[196:199], v157 offset:32768
	ds_read_b128 v[200:203], v157 offset:33792
	ds_read_b128 v[204:207], v157 offset:34816
	ds_read_b128 v[208:211], v157 offset:35840
	ds_read_b128 v[212:215], v157 offset:36864
	ds_read_b128 v[216:219], v157 offset:37888
	ds_read_b128 v[220:223], v157 offset:38912
	ds_read_b128 v[224:227], v157 offset:39936
	global_load_lds_dwordx4 v130, s[50:51]
	s_mov_b32 m0, s67
	s_nop 0
	global_load_lds_dwordx4 v134, s[50:51]
	s_waitcnt vmcnt(8)
	s_waitcnt lgkmcnt(0)
	s_barrier
	v_mfma_f32_16x16x32_bf16 v[126:129], v[160:163], v[196:199], v[126:129]
	v_mfma_f32_16x16x32_bf16 v[126:129], v[164:167], v[200:203], v[126:129]
	v_mfma_f32_16x16x32_bf16 v[122:125], v[168:171], v[196:199], v[122:125]
	v_mfma_f32_16x16x32_bf16 v[122:125], v[172:175], v[200:203], v[122:125]
	v_mfma_f32_16x16x32_bf16 v[118:121], v[176:179], v[196:199], v[118:121]
	v_mfma_f32_16x16x32_bf16 v[118:121], v[184:187], v[200:203], v[118:121]
	v_mfma_f32_16x16x32_bf16 v[114:117], v[188:191], v[196:199], v[114:117]
	v_mfma_f32_16x16x32_bf16 v[114:117], v[192:195], v[200:203], v[114:117]
	v_mfma_f32_16x16x32_bf16 v[110:113], v[160:163], v[204:207], v[110:113]
	v_mfma_f32_16x16x32_bf16 v[110:113], v[164:167], v[208:211], v[110:113]
	v_mfma_f32_16x16x32_bf16 v[106:109], v[168:171], v[204:207], v[106:109]
	v_mfma_f32_16x16x32_bf16 v[106:109], v[172:175], v[208:211], v[106:109]
	v_mfma_f32_16x16x32_bf16 v[102:105], v[176:179], v[204:207], v[102:105]
	v_mfma_f32_16x16x32_bf16 v[102:105], v[184:187], v[208:211], v[102:105]
	v_mfma_f32_16x16x32_bf16 v[98:101], v[188:191], v[204:207], v[98:101]
	v_mfma_f32_16x16x32_bf16 v[98:101], v[192:195], v[208:211], v[98:101]
	v_mfma_f32_16x16x32_bf16 v[94:97], v[160:163], v[212:215], v[94:97]
	v_mfma_f32_16x16x32_bf16 v[94:97], v[164:167], v[216:219], v[94:97]
	v_mfma_f32_16x16x32_bf16 v[90:93], v[168:171], v[212:215], v[90:93]
	v_mfma_f32_16x16x32_bf16 v[90:93], v[172:175], v[216:219], v[90:93]
	v_mfma_f32_16x16x32_bf16 v[86:89], v[176:179], v[212:215], v[86:89]
	v_mfma_f32_16x16x32_bf16 v[86:89], v[184:187], v[216:219], v[86:89]
	v_mfma_f32_16x16x32_bf16 v[82:85], v[188:191], v[212:215], v[82:85]
	v_mfma_f32_16x16x32_bf16 v[82:85], v[192:195], v[216:219], v[82:85]
	v_mfma_f32_16x16x32_bf16 v[78:81], v[160:163], v[220:223], v[78:81]
	v_mfma_f32_16x16x32_bf16 v[78:81], v[164:167], v[224:227], v[78:81]
	v_mfma_f32_16x16x32_bf16 v[74:77], v[168:171], v[220:223], v[74:77]
	v_mfma_f32_16x16x32_bf16 v[74:77], v[172:175], v[224:227], v[74:77]
	v_mfma_f32_16x16x32_bf16 v[70:73], v[176:179], v[220:223], v[70:73]
	v_mfma_f32_16x16x32_bf16 v[70:73], v[184:187], v[224:227], v[70:73]
	v_mfma_f32_16x16x32_bf16 v[66:69], v[188:191], v[220:223], v[66:69]
	v_mfma_f32_16x16x32_bf16 v[66:69], v[192:195], v[224:227], v[66:69]
	s_barrier
	s_add_i32 s50, s90, s27
	s_mov_b32 m0, s50
	ds_read_b128 v[196:199], v157 offset:49152
	ds_read_b128 v[200:203], v157 offset:50176
	ds_read_b128 v[204:207], v157 offset:51200
	ds_read_b128 v[208:211], v157 offset:52224
	ds_read_b128 v[212:215], v157 offset:53248
	ds_read_b128 v[216:219], v157 offset:54272
	ds_read_b128 v[220:223], v157 offset:55296
	ds_read_b128 v[224:227], v157 offset:56320
	global_load_lds_dwordx4 v132, s[98:99]
	s_add_i32 m0, s50, 0x2000
	s_add_u32 s48, s48, 0x100080
	s_addc_u32 s49, s49, 0
	s_add_i32 s50, s91, s27
	global_load_lds_dwordx4 v136, s[98:99]
	s_mov_b32 m0, s50
	s_nop 0
	global_load_lds_dwordx4 v132, s[48:49]
	s_add_i32 m0, s50, 0x2000
	s_nop 0
	global_load_lds_dwordx4 v136, s[48:49]
	s_mov_b32 m0, s69
	s_nop 0
	global_load_lds_dwordx4 v130, s[100:101]
	s_mov_b32 m0, s70
	s_nop 0
	global_load_lds_dwordx4 v134, s[100:101]
	s_waitcnt vmcnt(8)
	s_waitcnt lgkmcnt(0)
	s_barrier
	v_mfma_f32_16x16x32_bf16 v[62:65], v[160:163], v[196:199], v[62:65]
	v_mfma_f32_16x16x32_bf16 v[62:65], v[164:167], v[200:203], v[62:65]
	v_mfma_f32_16x16x32_bf16 v[58:61], v[168:171], v[196:199], v[58:61]
	v_mfma_f32_16x16x32_bf16 v[58:61], v[172:175], v[200:203], v[58:61]
	v_mfma_f32_16x16x32_bf16 v[54:57], v[176:179], v[196:199], v[54:57]
	v_mfma_f32_16x16x32_bf16 v[54:57], v[184:187], v[200:203], v[54:57]
	v_mfma_f32_16x16x32_bf16 v[46:49], v[188:191], v[196:199], v[46:49]
	v_mfma_f32_16x16x32_bf16 v[46:49], v[192:195], v[200:203], v[46:49]
	v_mfma_f32_16x16x32_bf16 v[50:53], v[160:163], v[204:207], v[50:53]
	v_mfma_f32_16x16x32_bf16 v[50:53], v[164:167], v[208:211], v[50:53]
	v_mfma_f32_16x16x32_bf16 v[42:45], v[168:171], v[204:207], v[42:45]
	v_mfma_f32_16x16x32_bf16 v[42:45], v[172:175], v[208:211], v[42:45]
	v_mfma_f32_16x16x32_bf16 v[38:41], v[176:179], v[204:207], v[38:41]
	v_mfma_f32_16x16x32_bf16 v[38:41], v[184:187], v[208:211], v[38:41]
	v_mfma_f32_16x16x32_bf16 v[30:33], v[188:191], v[204:207], v[30:33]
	v_mfma_f32_16x16x32_bf16 v[30:33], v[192:195], v[208:211], v[30:33]
	v_mfma_f32_16x16x32_bf16 v[34:37], v[160:163], v[212:215], v[34:37]
	v_mfma_f32_16x16x32_bf16 v[34:37], v[164:167], v[216:219], v[34:37]
	v_mfma_f32_16x16x32_bf16 v[26:29], v[168:171], v[212:215], v[26:29]
	v_mfma_f32_16x16x32_bf16 v[26:29], v[172:175], v[216:219], v[26:29]
	v_mfma_f32_16x16x32_bf16 v[22:25], v[176:179], v[212:215], v[22:25]
	v_mfma_f32_16x16x32_bf16 v[22:25], v[184:187], v[216:219], v[22:25]
	v_mfma_f32_16x16x32_bf16 v[14:17], v[188:191], v[212:215], v[14:17]
	v_mfma_f32_16x16x32_bf16 v[14:17], v[192:195], v[216:219], v[14:17]
	v_mfma_f32_16x16x32_bf16 v[18:21], v[160:163], v[220:223], v[18:21]
	v_mfma_f32_16x16x32_bf16 v[18:21], v[164:167], v[224:227], v[18:21]
	v_mfma_f32_16x16x32_bf16 v[10:13], v[168:171], v[220:223], v[10:13]
	v_mfma_f32_16x16x32_bf16 v[10:13], v[172:175], v[224:227], v[10:13]
	v_mfma_f32_16x16x32_bf16 v[6:9], v[176:179], v[220:223], v[6:9]
	v_mfma_f32_16x16x32_bf16 v[6:9], v[184:187], v[224:227], v[6:9]
	v_mfma_f32_16x16x32_bf16 v[2:5], v[188:191], v[220:223], v[2:5]
	v_mfma_f32_16x16x32_bf16 v[2:5], v[192:195], v[224:227], v[2:5]
	s_barrier
	s_add_i32 s89, s89, 2
	s_add_u32 s6, s6, 0x100
	s_addc_u32 s7, s7, 0
	s_add_u32 s87, s87, 0x100
	s_addc_u32 s88, s88, 0
	s_cmp_gt_u32 s89, 61
	s_cbranch_scc0 .LBB0_2494
	s_setprio 0
	s_and_b64 vcc, exec, s[38:39]
	s_cbranch_vccz .LBB0_2497
	s_barrier

.Lsprio_6:
	v_add_u32_e32 v246, 0x18000, v1
	v_add_u32_e32 v247, 0x1c000, v1
.LBB0_2635:
	ds_read_b128 v[130:133], v163
	ds_read_b128 v[134:137], v163 offset:1024
	ds_read_b128 v[138:141], v163 offset:2048
	ds_read_b128 v[142:145], v163 offset:3072
	ds_read_b128 v[146:149], v188
	ds_read_b128 v[150:153], v188 offset:1024
	ds_read_b128 v[174:177], v188 offset:2048
	ds_read_b128 v[178:181], v188 offset:3072
	s_add_u32 s48, s46, 0xfff00080
	s_addc_u32 s49, s47, -1
	s_cmp_eq_u32 s73, 60
	s_cselect_b32 s51, s22, s49
	s_cselect_b32 s50, s41, s48
	s_cselect_b32 s49, s39, s72
	s_cselect_b32 s48, s70, s71
	s_add_i32 m0, s13, 0xc000
	ds_read_b128 v[184:187], v189
	ds_read_b128 v[192:195], v189 offset:1024
	ds_read_b128 v[196:199], v189 offset:2048
	ds_read_b128 v[200:203], v189 offset:3072
	ds_read_b128 v[204:207], v189 offset:4096
	ds_read_b128 v[208:211], v189 offset:5120
	ds_read_b128 v[212:215], v189 offset:6144
	ds_read_b128 v[216:219], v189 offset:7168
	global_load_lds_dwordx4 v166, s[46:47]
	s_add_i32 m0, s13, 0xe000
	s_nop 0
	global_load_lds_dwordx4 v168, s[46:47]
	s_waitcnt vmcnt(8)
	s_waitcnt lgkmcnt(0)
	s_barrier
	v_mfma_f32_16x16x32_bf16 v[126:129], v[130:133], v[184:187], v[126:129]
	v_mfma_f32_16x16x32_bf16 v[126:129], v[134:137], v[192:195], v[126:129]
	v_mfma_f32_16x16x32_bf16 v[122:125], v[138:141], v[184:187], v[122:125]
	v_mfma_f32_16x16x32_bf16 v[122:125], v[142:145], v[192:195], v[122:125]
	v_mfma_f32_16x16x32_bf16 v[118:121], v[146:149], v[184:187], v[118:121]
	v_mfma_f32_16x16x32_bf16 v[118:121], v[150:153], v[192:195], v[118:121]
	v_mfma_f32_16x16x32_bf16 v[114:117], v[174:177], v[184:187], v[114:117]
	v_mfma_f32_16x16x32_bf16 v[114:117], v[178:181], v[192:195], v[114:117]
	v_mfma_f32_16x16x32_bf16 v[110:113], v[130:133], v[196:199], v[110:113]
	v_mfma_f32_16x16x32_bf16 v[110:113], v[134:137], v[200:203], v[110:113]
	v_mfma_f32_16x16x32_bf16 v[106:109], v[138:141], v[196:199], v[106:109]
	v_mfma_f32_16x16x32_bf16 v[106:109], v[142:145], v[200:203], v[106:109]
	v_mfma_f32_16x16x32_bf16 v[102:105], v[146:149], v[196:199], v[102:105]
	v_mfma_f32_16x16x32_bf16 v[102:105], v[150:153], v[200:203], v[102:105]
	v_mfma_f32_16x16x32_bf16 v[98:101], v[174:177], v[196:199], v[98:101]
	v_mfma_f32_16x16x32_bf16 v[98:101], v[178:181], v[200:203], v[98:101]
	v_mfma_f32_16x16x32_bf16 v[94:97], v[130:133], v[204:207], v[94:97]
	v_mfma_f32_16x16x32_bf16 v[94:97], v[134:137], v[208:211], v[94:97]
	v_mfma_f32_16x16x32_bf16 v[90:93], v[138:141], v[204:207], v[90:93]
	v_mfma_f32_16x16x32_bf16 v[90:93], v[142:145], v[208:211], v[90:93]
	v_mfma_f32_16x16x32_bf16 v[86:89], v[146:149], v[204:207], v[86:89]
	v_mfma_f32_16x16x32_bf16 v[86:89], v[150:153], v[208:211], v[86:89]
	v_mfma_f32_16x16x32_bf16 v[82:85], v[174:177], v[204:207], v[82:85]
	v_mfma_f32_16x16x32_bf16 v[82:85], v[178:181], v[208:211], v[82:85]
	v_mfma_f32_16x16x32_bf16 v[78:81], v[130:133], v[212:215], v[78:81]
	v_mfma_f32_16x16x32_bf16 v[78:81], v[134:137], v[216:219], v[78:81]
	v_mfma_f32_16x16x32_bf16 v[74:77], v[138:141], v[212:215], v[74:77]
	v_mfma_f32_16x16x32_bf16 v[74:77], v[142:145], v[216:219], v[74:77]
	v_mfma_f32_16x16x32_bf16 v[70:73], v[146:149], v[212:215], v[70:73]
	v_mfma_f32_16x16x32_bf16 v[70:73], v[150:153], v[216:219], v[70:73]
	v_mfma_f32_16x16x32_bf16 v[66:69], v[174:177], v[212:215], v[66:69]
	v_mfma_f32_16x16x32_bf16 v[66:69], v[178:181], v[216:219], v[66:69]
	s_barrier
	s_add_i32 s74, s67, s3
	s_add_u32 s98, s48, 0x80
	s_addc_u32 s99, s49, 0
	s_mov_b32 m0, s74
	ds_read_b128 v[184:187], v189 offset:16384
	ds_read_b128 v[192:195], v189 offset:17408
	ds_read_b128 v[196:199], v189 offset:18432
	ds_read_b128 v[200:203], v189 offset:19456
	ds_read_b128 v[204:207], v189 offset:20480
	ds_read_b128 v[208:211], v189 offset:21504
	ds_read_b128 v[212:215], v189 offset:22528
	ds_read_b128 v[216:219], v189 offset:23552
	global_load_lds_dwordx4 v156, s[48:49]
	s_add_i32 m0, s74, 0x2000
	s_add_u32 s74, s48, 0x100000
	s_addc_u32 s75, s49, 0
	s_add_i32 s76, s68, s3
	global_load_lds_dwordx4 v160, s[48:49]
	s_mov_b32 m0, s76
	global_load_lds_dwordx4 v156, s[74:75]
	s_add_i32 m0, s76, 0x2000
	s_nop 0
	global_load_lds_dwordx4 v160, s[74:75]
	s_add_u32 s100, s50, 0x80
	s_addc_u32 s101, s51, 0
	s_mov_b32 m0, s13
	s_nop 0
	global_load_lds_dwordx4 v154, s[50:51]
	s_mov_b32 m0, s21
	s_nop 0
	global_load_lds_dwordx4 v158, s[50:51]
	s_waitcnt vmcnt(8)
	s_waitcnt lgkmcnt(0)
	s_barrier
	v_mfma_f32_16x16x32_bf16 v[62:65], v[130:133], v[184:187], v[62:65]
	v_mfma_f32_16x16x32_bf16 v[62:65], v[134:137], v[192:195], v[62:65]
	v_mfma_f32_16x16x32_bf16 v[58:61], v[138:141], v[184:187], v[58:61]
	v_mfma_f32_16x16x32_bf16 v[58:61], v[142:145], v[192:195], v[58:61]
	v_mfma_f32_16x16x32_bf16 v[54:57], v[146:149], v[184:187], v[54:57]
	v_mfma_f32_16x16x32_bf16 v[54:57], v[150:153], v[192:195], v[54:57]
	v_mfma_f32_16x16x32_bf16 v[50:53], v[174:177], v[184:187], v[50:53]
	v_mfma_f32_16x16x32_bf16 v[50:53], v[178:181], v[192:195], v[50:53]
	v_mfma_f32_16x16x32_bf16 v[46:49], v[130:133], v[196:199], v[46:49]
	v_mfma_f32_16x16x32_bf16 v[46:49], v[134:137], v[200:203], v[46:49]
	v_mfma_f32_16x16x32_bf16 v[42:45], v[138:141], v[196:199], v[42:45]
	v_mfma_f32_16x16x32_bf16 v[42:45], v[142:145], v[200:203], v[42:45]
	v_mfma_f32_16x16x32_bf16 v[38:41], v[146:149], v[196:199], v[38:41]
	v_mfma_f32_16x16x32_bf16 v[38:41], v[150:153], v[200:203], v[38:41]
	v_mfma_f32_16x16x32_bf16 v[34:37], v[174:177], v[196:199], v[34:37]
	v_mfma_f32_16x16x32_bf16 v[34:37], v[178:181], v[200:203], v[34:37]
	v_mfma_f32_16x16x32_bf16 v[30:33], v[130:133], v[204:207], v[30:33]
	v_mfma_f32_16x16x32_bf16 v[30:33], v[134:137], v[208:211], v[30:33]
	v_mfma_f32_16x16x32_bf16 v[26:29], v[138:141], v[204:207], v[26:29]
	v_mfma_f32_16x16x32_bf16 v[26:29], v[142:145], v[208:211], v[26:29]
	v_mfma_f32_16x16x32_bf16 v[22:25], v[146:149], v[204:207], v[22:25]
	v_mfma_f32_16x16x32_bf16 v[22:25], v[150:153], v[208:211], v[22:25]
	v_mfma_f32_16x16x32_bf16 v[18:21], v[174:177], v[204:207], v[18:21]
	v_mfma_f32_16x16x32_bf16 v[18:21], v[178:181], v[208:211], v[18:21]
	v_mfma_f32_16x16x32_bf16 v[14:17], v[130:133], v[212:215], v[14:17]
	v_mfma_f32_16x16x32_bf16 v[14:17], v[134:137], v[216:219], v[14:17]
	v_mfma_f32_16x16x32_bf16 v[10:13], v[138:141], v[212:215], v[10:13]
	v_mfma_f32_16x16x32_bf16 v[10:13], v[142:145], v[216:219], v[10:13]
	v_mfma_f32_16x16x32_bf16 v[6:9], v[146:149], v[212:215], v[6:9]
	v_mfma_f32_16x16x32_bf16 v[6:9], v[150:153], v[216:219], v[6:9]
	v_mfma_f32_16x16x32_bf16 v[2:5], v[174:177], v[212:215], v[2:5]
	v_mfma_f32_16x16x32_bf16 v[2:5], v[178:181], v[216:219], v[2:5]
	s_barrier
	s_add_i32 s74, 0, 0x18000
	s_add_i32 s75, 0, 0x1c000
	ds_read_b128 v[130:133], v246
	ds_read_b128 v[134:137], v246 offset:1024
	ds_read_b128 v[138:141], v246 offset:2048
	ds_read_b128 v[142:145], v246 offset:3072
	ds_read_b128 v[146:149], v247
	ds_read_b128 v[150:153], v247 offset:1024
	ds_read_b128 v[174:177], v247 offset:2048
	ds_read_b128 v[178:181], v247 offset:3072
	s_add_u32 s50, s50, 0x100000
	s_addc_u32 s51, s51, 0
	s_mov_b32 m0, s33
	ds_read_b128 v[184:187], v189 offset:32768
	ds_read_b128 v[192:195], v189 offset:33792
	ds_read_b128 v[196:199], v189 offset:34816
	ds_read_b128 v[200:203], v189 offset:35840
	ds_read_b128 v[204:207], v189 offset:36864
	ds_read_b128 v[208:211], v189 offset:37888
	ds_read_b128 v[212:215], v189 offset:38912
	ds_read_b128 v[216:219], v189 offset:39936
	global_load_lds_dwordx4 v154, s[50:51]
	s_mov_b32 m0, s35
	s_nop 0
	global_load_lds_dwordx4 v158, s[50:51]
	s_waitcnt vmcnt(8)
	s_waitcnt lgkmcnt(0)
	s_barrier
	v_mfma_f32_16x16x32_bf16 v[126:129], v[130:133], v[184:187], v[126:129]
	v_mfma_f32_16x16x32_bf16 v[126:129], v[134:137], v[192:195], v[126:129]
	v_mfma_f32_16x16x32_bf16 v[122:125], v[138:141], v[184:187], v[122:125]
	v_mfma_f32_16x16x32_bf16 v[122:125], v[142:145], v[192:195], v[122:125]
	v_mfma_f32_16x16x32_bf16 v[118:121], v[146:149], v[184:187], v[118:121]
	v_mfma_f32_16x16x32_bf16 v[118:121], v[150:153], v[192:195], v[118:121]
	v_mfma_f32_16x16x32_bf16 v[114:117], v[174:177], v[184:187], v[114:117]
	v_mfma_f32_16x16x32_bf16 v[114:117], v[178:181], v[192:195], v[114:117]
	v_mfma_f32_16x16x32_bf16 v[110:113], v[130:133], v[196:199], v[110:113]
	v_mfma_f32_16x16x32_bf16 v[110:113], v[134:137], v[200:203], v[110:113]
	v_mfma_f32_16x16x32_bf16 v[106:109], v[138:141], v[196:199], v[106:109]
	v_mfma_f32_16x16x32_bf16 v[106:109], v[142:145], v[200:203], v[106:109]
	v_mfma_f32_16x16x32_bf16 v[102:105], v[146:149], v[196:199], v[102:105]
	v_mfma_f32_16x16x32_bf16 v[102:105], v[150:153], v[200:203], v[102:105]
	v_mfma_f32_16x16x32_bf16 v[98:101], v[174:177], v[196:199], v[98:101]
	v_mfma_f32_16x16x32_bf16 v[98:101], v[178:181], v[200:203], v[98:101]
	v_mfma_f32_16x16x32_bf16 v[94:97], v[130:133], v[204:207], v[94:97]
	v_mfma_f32_16x16x32_bf16 v[94:97], v[134:137], v[208:211], v[94:97]
	v_mfma_f32_16x16x32_bf16 v[90:93], v[138:141], v[204:207], v[90:93]
	v_mfma_f32_16x16x32_bf16 v[90:93], v[142:145], v[208:211], v[90:93]
	v_mfma_f32_16x16x32_bf16 v[86:89], v[146:149], v[204:207], v[86:89]
	v_mfma_f32_16x16x32_bf16 v[86:89], v[150:153], v[208:211], v[86:89]
	v_mfma_f32_16x16x32_bf16 v[82:85], v[174:177], v[204:207], v[82:85]
	v_mfma_f32_16x16x32_bf16 v[82:85], v[178:181], v[208:211], v[82:85]
	v_mfma_f32_16x16x32_bf16 v[78:81], v[130:133], v[212:215], v[78:81]
	v_mfma_f32_16x16x32_bf16 v[78:81], v[134:137], v[216:219], v[78:81]
	v_mfma_f32_16x16x32_bf16 v[74:77], v[138:141], v[212:215], v[74:77]
	v_mfma_f32_16x16x32_bf16 v[74:77], v[142:145], v[216:219], v[74:77]
	v_mfma_f32_16x16x32_bf16 v[70:73], v[146:149], v[212:215], v[70:73]
	v_mfma_f32_16x16x32_bf16 v[70:73], v[150:153], v[216:219], v[70:73]
	v_mfma_f32_16x16x32_bf16 v[66:69], v[174:177], v[212:215], v[66:69]
	v_mfma_f32_16x16x32_bf16 v[66:69], v[178:181], v[216:219], v[66:69]
	s_barrier
	s_add_i32 s50, s74, s3
	s_mov_b32 m0, s50
	ds_read_b128 v[184:187], v189 offset:49152
	ds_read_b128 v[192:195], v189 offset:50176
	ds_read_b128 v[196:199], v189 offset:51200
	ds_read_b128 v[200:203], v189 offset:52224
	ds_read_b128 v[204:207], v189 offset:53248
	ds_read_b128 v[208:211], v189 offset:54272
	ds_read_b128 v[212:215], v189 offset:55296
	ds_read_b128 v[216:219], v189 offset:56320
	global_load_lds_dwordx4 v156, s[98:99]
	s_add_i32 m0, s50, 0x2000
	s_add_u32 s48, s48, 0x100080
	s_addc_u32 s49, s49, 0
	s_add_i32 s50, s75, s3
	global_load_lds_dwordx4 v160, s[98:99]
	s_mov_b32 m0, s50
	s_nop 0
	global_load_lds_dwordx4 v156, s[48:49]
	s_add_i32 m0, s50, 0x2000
	s_nop 0
	global_load_lds_dwordx4 v160, s[48:49]
	s_mov_b32 m0, s62
	s_nop 0
	global_load_lds_dwordx4 v154, s[100:101]
	s_mov_b32 m0, s63
	s_nop 0
	global_load_lds_dwordx4 v158, s[100:101]
	s_waitcnt vmcnt(8)
	s_waitcnt lgkmcnt(0)
	s_barrier
	v_mfma_f32_16x16x32_bf16 v[62:65], v[130:133], v[184:187], v[62:65]
	v_mfma_f32_16x16x32_bf16 v[62:65], v[134:137], v[192:195], v[62:65]
	v_mfma_f32_16x16x32_bf16 v[58:61], v[138:141], v[184:187], v[58:61]
	v_mfma_f32_16x16x32_bf16 v[58:61], v[142:145], v[192:195], v[58:61]
	v_mfma_f32_16x16x32_bf16 v[54:57], v[146:149], v[184:187], v[54:57]
	v_mfma_f32_16x16x32_bf16 v[54:57], v[150:153], v[192:195], v[54:57]
	v_mfma_f32_16x16x32_bf16 v[50:53], v[174:177], v[184:187], v[50:53]
	v_mfma_f32_16x16x32_bf16 v[50:53], v[178:181], v[192:195], v[50:53]
	v_mfma_f32_16x16x32_bf16 v[46:49], v[130:133], v[196:199], v[46:49]
	v_mfma_f32_16x16x32_bf16 v[46:49], v[134:137], v[200:203], v[46:49]
	v_mfma_f32_16x16x32_bf16 v[42:45], v[138:141], v[196:199], v[42:45]
	v_mfma_f32_16x16x32_bf16 v[42:45], v[142:145], v[200:203], v[42:45]
	v_mfma_f32_16x16x32_bf16 v[38:41], v[146:149], v[196:199], v[38:41]
	v_mfma_f32_16x16x32_bf16 v[38:41], v[150:153], v[200:203], v[38:41]
	v_mfma_f32_16x16x32_bf16 v[34:37], v[174:177], v[196:199], v[34:37]
	v_mfma_f32_16x16x32_bf16 v[34:37], v[178:181], v[200:203], v[34:37]
	v_mfma_f32_16x16x32_bf16 v[30:33], v[130:133], v[204:207], v[30:33]
	v_mfma_f32_16x16x32_bf16 v[30:33], v[134:137], v[208:211], v[30:33]
	v_mfma_f32_16x16x32_bf16 v[26:29], v[138:141], v[204:207], v[26:29]
	v_mfma_f32_16x16x32_bf16 v[26:29], v[142:145], v[208:211], v[26:29]
	v_mfma_f32_16x16x32_bf16 v[22:25], v[146:149], v[204:207], v[22:25]
	v_mfma_f32_16x16x32_bf16 v[22:25], v[150:153], v[208:211], v[22:25]
	v_mfma_f32_16x16x32_bf16 v[18:21], v[174:177], v[204:207], v[18:21]
	v_mfma_f32_16x16x32_bf16 v[18:21], v[178:181], v[208:211], v[18:21]
	v_mfma_f32_16x16x32_bf16 v[14:17], v[130:133], v[212:215], v[14:17]
	v_mfma_f32_16x16x32_bf16 v[14:17], v[134:137], v[216:219], v[14:17]
	v_mfma_f32_16x16x32_bf16 v[10:13], v[138:141], v[212:215], v[10:13]
	v_mfma_f32_16x16x32_bf16 v[10:13], v[142:145], v[216:219], v[10:13]
	v_mfma_f32_16x16x32_bf16 v[6:9], v[146:149], v[212:215], v[6:9]
	v_mfma_f32_16x16x32_bf16 v[6:9], v[150:153], v[216:219], v[6:9]
	v_mfma_f32_16x16x32_bf16 v[2:5], v[174:177], v[212:215], v[2:5]
	v_mfma_f32_16x16x32_bf16 v[2:5], v[178:181], v[216:219], v[2:5]
	s_barrier
	s_add_i32 s73, s73, 2
	s_add_u32 s46, s46, 0x100
	s_addc_u32 s47, s47, 0
	s_add_u32 s71, s71, 0x100
	s_addc_u32 s72, s72, 0
	s_cmp_gt_u32 s73, 61
	s_cbranch_scc0 .LBB0_2635
	s_setprio 0
	s_and_b64 vcc, exec, s[36:37]
	s_cbranch_vccz .LBB0_2638
	s_barrier

.LBB0_2720:
	ds_read_b128 v[148:151], v159
	ds_read_b128 v[164:167], v159 offset:1024
	ds_read_b128 v[168:171], v159 offset:2048
	ds_read_b128 v[172:175], v159 offset:3072
	ds_read_b128 v[176:179], v160
	ds_read_b128 v[184:187], v160 offset:1024
	ds_read_b128 v[188:191], v160 offset:2048
	ds_read_b128 v[192:195], v160 offset:3072
	s_add_u32 s40, s6, 0xfff00080
	s_addc_u32 s41, s7, -1
	s_cmp_eq_u32 s82, 60
	s_cselect_b32 s43, s29, s41
	s_cselect_b32 s42, s78, s40
	s_cselect_b32 s41, s27, s81
	s_cselect_b32 s40, s79, s80
	s_add_i32 m0, s44, 0xc000
	ds_read_b128 v[196:199], v161
	ds_read_b128 v[200:203], v161 offset:1024
	ds_read_b128 v[204:207], v161 offset:2048
	ds_read_b128 v[208:211], v161 offset:3072
	ds_read_b128 v[212:215], v161 offset:4096
	ds_read_b128 v[216:219], v161 offset:5120
	ds_read_b128 v[220:223], v161 offset:6144
	ds_read_b128 v[224:227], v161 offset:7168
	global_load_lds_dwordx4 v140, s[6:7]
	s_add_i32 m0, s44, 0xe000
	s_nop 0
	global_load_lds_dwordx4 v142, s[6:7]
	s_waitcnt vmcnt(8)
	s_waitcnt lgkmcnt(0)
	s_barrier
	v_mfma_f32_16x16x32_bf16 v[126:129], v[148:151], v[196:199], v[126:129]
	v_mfma_f32_16x16x32_bf16 v[126:129], v[164:167], v[200:203], v[126:129]
	v_mfma_f32_16x16x32_bf16 v[118:121], v[168:171], v[196:199], v[118:121]
	v_mfma_f32_16x16x32_bf16 v[118:121], v[172:175], v[200:203], v[118:121]
	v_mfma_f32_16x16x32_bf16 v[122:125], v[176:179], v[196:199], v[122:125]
	v_mfma_f32_16x16x32_bf16 v[122:125], v[184:187], v[200:203], v[122:125]
	v_mfma_f32_16x16x32_bf16 v[114:117], v[188:191], v[196:199], v[114:117]
	v_mfma_f32_16x16x32_bf16 v[114:117], v[192:195], v[200:203], v[114:117]
	v_mfma_f32_16x16x32_bf16 v[110:113], v[148:151], v[204:207], v[110:113]
	v_mfma_f32_16x16x32_bf16 v[110:113], v[164:167], v[208:211], v[110:113]
	v_mfma_f32_16x16x32_bf16 v[102:105], v[168:171], v[204:207], v[102:105]
	v_mfma_f32_16x16x32_bf16 v[102:105], v[172:175], v[208:211], v[102:105]
	v_mfma_f32_16x16x32_bf16 v[106:109], v[176:179], v[204:207], v[106:109]
	v_mfma_f32_16x16x32_bf16 v[106:109], v[184:187], v[208:211], v[106:109]
	v_mfma_f32_16x16x32_bf16 v[98:101], v[188:191], v[204:207], v[98:101]
	v_mfma_f32_16x16x32_bf16 v[98:101], v[192:195], v[208:211], v[98:101]
	v_mfma_f32_16x16x32_bf16 v[94:97], v[148:151], v[212:215], v[94:97]
	v_mfma_f32_16x16x32_bf16 v[94:97], v[164:167], v[216:219], v[94:97]
	v_mfma_f32_16x16x32_bf16 v[86:89], v[168:171], v[212:215], v[86:89]
	v_mfma_f32_16x16x32_bf16 v[86:89], v[172:175], v[216:219], v[86:89]
	v_mfma_f32_16x16x32_bf16 v[90:93], v[176:179], v[212:215], v[90:93]
	v_mfma_f32_16x16x32_bf16 v[90:93], v[184:187], v[216:219], v[90:93]
	v_mfma_f32_16x16x32_bf16 v[82:85], v[188:191], v[212:215], v[82:85]
	v_mfma_f32_16x16x32_bf16 v[82:85], v[192:195], v[216:219], v[82:85]
	v_mfma_f32_16x16x32_bf16 v[78:81], v[148:151], v[220:223], v[78:81]
	v_mfma_f32_16x16x32_bf16 v[78:81], v[164:167], v[224:227], v[78:81]
	v_mfma_f32_16x16x32_bf16 v[70:73], v[168:171], v[220:223], v[70:73]
	v_mfma_f32_16x16x32_bf16 v[70:73], v[172:175], v[224:227], v[70:73]
	v_mfma_f32_16x16x32_bf16 v[74:77], v[176:179], v[220:223], v[74:77]
	v_mfma_f32_16x16x32_bf16 v[74:77], v[184:187], v[224:227], v[74:77]
	v_mfma_f32_16x16x32_bf16 v[66:69], v[188:191], v[220:223], v[66:69]
	v_mfma_f32_16x16x32_bf16 v[66:69], v[192:195], v[224:227], v[66:69]
	s_barrier
	s_add_i32 s83, s68, s13
	s_add_u32 s98, s40, 0x80
	s_addc_u32 s99, s41, 0
	s_mov_b32 m0, s83
	ds_read_b128 v[196:199], v161 offset:16384
	ds_read_b128 v[200:203], v161 offset:17408
	ds_read_b128 v[204:207], v161 offset:18432
	ds_read_b128 v[208:211], v161 offset:19456
	ds_read_b128 v[212:215], v161 offset:20480
	ds_read_b128 v[216:219], v161 offset:21504
	ds_read_b128 v[220:223], v161 offset:22528
	ds_read_b128 v[224:227], v161 offset:23552
	global_load_lds_dwordx4 v132, s[40:41]
	s_add_i32 m0, s83, 0x2000
	s_add_u32 s84, s40, 0x100000
	s_addc_u32 s85, s41, 0
	s_add_i32 s83, s69, s13
	global_load_lds_dwordx4 v136, s[40:41]
	s_mov_b32 m0, s83
	global_load_lds_dwordx4 v132, s[84:85]
	s_add_i32 m0, s83, 0x2000
	s_nop 0
	global_load_lds_dwordx4 v136, s[84:85]
	s_add_u32 s100, s42, 0x80
	s_addc_u32 s101, s43, 0
	s_mov_b32 m0, s44
	s_nop 0
	global_load_lds_dwordx4 v130, s[42:43]
	s_mov_b32 m0, s45
	s_nop 0
	global_load_lds_dwordx4 v134, s[42:43]
	s_waitcnt vmcnt(8)
	s_waitcnt lgkmcnt(0)
	s_barrier
	v_mfma_f32_16x16x32_bf16 v[62:65], v[148:151], v[196:199], v[62:65]
	v_mfma_f32_16x16x32_bf16 v[62:65], v[164:167], v[200:203], v[62:65]
	v_mfma_f32_16x16x32_bf16 v[54:57], v[168:171], v[196:199], v[54:57]
	v_mfma_f32_16x16x32_bf16 v[54:57], v[172:175], v[200:203], v[54:57]
	v_mfma_f32_16x16x32_bf16 v[58:61], v[176:179], v[196:199], v[58:61]
	v_mfma_f32_16x16x32_bf16 v[58:61], v[184:187], v[200:203], v[58:61]
	v_mfma_f32_16x16x32_bf16 v[50:53], v[188:191], v[196:199], v[50:53]
	v_mfma_f32_16x16x32_bf16 v[50:53], v[192:195], v[200:203], v[50:53]
	v_mfma_f32_16x16x32_bf16 v[46:49], v[148:151], v[204:207], v[46:49]
	v_mfma_f32_16x16x32_bf16 v[46:49], v[164:167], v[208:211], v[46:49]
	v_mfma_f32_16x16x32_bf16 v[38:41], v[168:171], v[204:207], v[38:41]
	v_mfma_f32_16x16x32_bf16 v[38:41], v[172:175], v[208:211], v[38:41]
	v_mfma_f32_16x16x32_bf16 v[42:45], v[176:179], v[204:207], v[42:45]
	v_mfma_f32_16x16x32_bf16 v[42:45], v[184:187], v[208:211], v[42:45]
	v_mfma_f32_16x16x32_bf16 v[34:37], v[188:191], v[204:207], v[34:37]
	v_mfma_f32_16x16x32_bf16 v[34:37], v[192:195], v[208:211], v[34:37]
	v_mfma_f32_16x16x32_bf16 v[30:33], v[148:151], v[212:215], v[30:33]
	v_mfma_f32_16x16x32_bf16 v[30:33], v[164:167], v[216:219], v[30:33]
	v_mfma_f32_16x16x32_bf16 v[22:25], v[168:171], v[212:215], v[22:25]
	v_mfma_f32_16x16x32_bf16 v[22:25], v[172:175], v[216:219], v[22:25]
	v_mfma_f32_16x16x32_bf16 v[26:29], v[176:179], v[212:215], v[26:29]
	v_mfma_f32_16x16x32_bf16 v[26:29], v[184:187], v[216:219], v[26:29]
	v_mfma_f32_16x16x32_bf16 v[18:21], v[188:191], v[212:215], v[18:21]
	v_mfma_f32_16x16x32_bf16 v[18:21], v[192:195], v[216:219], v[18:21]
	v_mfma_f32_16x16x32_bf16 v[14:17], v[148:151], v[220:223], v[14:17]
	v_mfma_f32_16x16x32_bf16 v[14:17], v[164:167], v[224:227], v[14:17]
	v_mfma_f32_16x16x32_bf16 v[6:9], v[168:171], v[220:223], v[6:9]
	v_mfma_f32_16x16x32_bf16 v[6:9], v[172:175], v[224:227], v[6:9]
	v_mfma_f32_16x16x32_bf16 v[10:13], v[176:179], v[220:223], v[10:13]
	v_mfma_f32_16x16x32_bf16 v[10:13], v[184:187], v[224:227], v[10:13]
	v_mfma_f32_16x16x32_bf16 v[2:5], v[188:191], v[220:223], v[2:5]
	v_mfma_f32_16x16x32_bf16 v[2:5], v[192:195], v[224:227], v[2:5]
	s_barrier
	s_add_i32 s83, 0, 0x18000
	s_add_i32 s84, 0, 0x1c000
	ds_read_b128 v[148:151], v246
	ds_read_b128 v[164:167], v246 offset:1024
	ds_read_b128 v[168:171], v246 offset:2048
	ds_read_b128 v[172:175], v246 offset:3072
	ds_read_b128 v[176:179], v247
	ds_read_b128 v[184:187], v247 offset:1024
	ds_read_b128 v[188:191], v247 offset:2048
	ds_read_b128 v[192:195], v247 offset:3072
	s_add_u32 s42, s42, 0x100000
	s_addc_u32 s43, s43, 0
	s_mov_b32 m0, s46
	ds_read_b128 v[196:199], v161 offset:32768
	ds_read_b128 v[200:203], v161 offset:33792
	ds_read_b128 v[204:207], v161 offset:34816
	ds_read_b128 v[208:211], v161 offset:35840
	ds_read_b128 v[212:215], v161 offset:36864
	ds_read_b128 v[216:219], v161 offset:37888
	ds_read_b128 v[220:223], v161 offset:38912
	ds_read_b128 v[224:227], v161 offset:39936
	global_load_lds_dwordx4 v130, s[42:43]
	s_mov_b32 m0, s47
	s_nop 0
	global_load_lds_dwordx4 v134, s[42:43]
	s_waitcnt vmcnt(8)
	s_waitcnt lgkmcnt(0)
	s_barrier
	v_mfma_f32_16x16x32_bf16 v[126:129], v[148:151], v[196:199], v[126:129]
	v_mfma_f32_16x16x32_bf16 v[126:129], v[164:167], v[200:203], v[126:129]
	v_mfma_f32_16x16x32_bf16 v[118:121], v[168:171], v[196:199], v[118:121]
	v_mfma_f32_16x16x32_bf16 v[118:121], v[172:175], v[200:203], v[118:121]
	v_mfma_f32_16x16x32_bf16 v[122:125], v[176:179], v[196:199], v[122:125]
	v_mfma_f32_16x16x32_bf16 v[122:125], v[184:187], v[200:203], v[122:125]
	v_mfma_f32_16x16x32_bf16 v[114:117], v[188:191], v[196:199], v[114:117]
	v_mfma_f32_16x16x32_bf16 v[114:117], v[192:195], v[200:203], v[114:117]
	v_mfma_f32_16x16x32_bf16 v[110:113], v[148:151], v[204:207], v[110:113]
	v_mfma_f32_16x16x32_bf16 v[110:113], v[164:167], v[208:211], v[110:113]
	v_mfma_f32_16x16x32_bf16 v[102:105], v[168:171], v[204:207], v[102:105]
	v_mfma_f32_16x16x32_bf16 v[102:105], v[172:175], v[208:211], v[102:105]
	v_mfma_f32_16x16x32_bf16 v[106:109], v[176:179], v[204:207], v[106:109]
	v_mfma_f32_16x16x32_bf16 v[106:109], v[184:187], v[208:211], v[106:109]
	v_mfma_f32_16x16x32_bf16 v[98:101], v[188:191], v[204:207], v[98:101]
	v_mfma_f32_16x16x32_bf16 v[98:101], v[192:195], v[208:211], v[98:101]
	v_mfma_f32_16x16x32_bf16 v[94:97], v[148:151], v[212:215], v[94:97]
	v_mfma_f32_16x16x32_bf16 v[94:97], v[164:167], v[216:219], v[94:97]
	v_mfma_f32_16x16x32_bf16 v[86:89], v[168:171], v[212:215], v[86:89]
	v_mfma_f32_16x16x32_bf16 v[86:89], v[172:175], v[216:219], v[86:89]
	v_mfma_f32_16x16x32_bf16 v[90:93], v[176:179], v[212:215], v[90:93]
	v_mfma_f32_16x16x32_bf16 v[90:93], v[184:187], v[216:219], v[90:93]
	v_mfma_f32_16x16x32_bf16 v[82:85], v[188:191], v[212:215], v[82:85]
	v_mfma_f32_16x16x32_bf16 v[82:85], v[192:195], v[216:219], v[82:85]
	v_mfma_f32_16x16x32_bf16 v[78:81], v[148:151], v[220:223], v[78:81]
	v_mfma_f32_16x16x32_bf16 v[78:81], v[164:167], v[224:227], v[78:81]
	v_mfma_f32_16x16x32_bf16 v[70:73], v[168:171], v[220:223], v[70:73]
	v_mfma_f32_16x16x32_bf16 v[70:73], v[172:175], v[224:227], v[70:73]
	v_mfma_f32_16x16x32_bf16 v[74:77], v[176:179], v[220:223], v[74:77]
	v_mfma_f32_16x16x32_bf16 v[74:77], v[184:187], v[224:227], v[74:77]
	v_mfma_f32_16x16x32_bf16 v[66:69], v[188:191], v[220:223], v[66:69]
	v_mfma_f32_16x16x32_bf16 v[66:69], v[192:195], v[224:227], v[66:69]
	s_barrier
	s_add_i32 s42, s83, s13
	s_mov_b32 m0, s42
	ds_read_b128 v[196:199], v161 offset:49152
	ds_read_b128 v[200:203], v161 offset:50176
	ds_read_b128 v[204:207], v161 offset:51200
	ds_read_b128 v[208:211], v161 offset:52224
	ds_read_b128 v[212:215], v161 offset:53248
	ds_read_b128 v[216:219], v161 offset:54272
	ds_read_b128 v[220:223], v161 offset:55296
	ds_read_b128 v[224:227], v161 offset:56320
	global_load_lds_dwordx4 v132, s[98:99]
	s_add_i32 m0, s42, 0x2000
	s_add_u32 s40, s40, 0x100080
	s_addc_u32 s41, s41, 0
	s_add_i32 s42, s84, s13
	global_load_lds_dwordx4 v136, s[98:99]
	s_mov_b32 m0, s42
	s_nop 0
	global_load_lds_dwordx4 v132, s[40:41]
	s_add_i32 m0, s42, 0x2000
	s_nop 0
	global_load_lds_dwordx4 v136, s[40:41]
	s_mov_b32 m0, s59
	s_nop 0
	global_load_lds_dwordx4 v130, s[100:101]
	s_mov_b32 m0, s62
	s_nop 0
	global_load_lds_dwordx4 v134, s[100:101]
	s_waitcnt vmcnt(8)
	s_waitcnt lgkmcnt(0)
	s_barrier
	v_mfma_f32_16x16x32_bf16 v[62:65], v[148:151], v[196:199], v[62:65]
	v_mfma_f32_16x16x32_bf16 v[62:65], v[164:167], v[200:203], v[62:65]
	v_mfma_f32_16x16x32_bf16 v[54:57], v[168:171], v[196:199], v[54:57]
	v_mfma_f32_16x16x32_bf16 v[54:57], v[172:175], v[200:203], v[54:57]
	v_mfma_f32_16x16x32_bf16 v[58:61], v[176:179], v[196:199], v[58:61]
	v_mfma_f32_16x16x32_bf16 v[58:61], v[184:187], v[200:203], v[58:61]
	v_mfma_f32_16x16x32_bf16 v[50:53], v[188:191], v[196:199], v[50:53]
	v_mfma_f32_16x16x32_bf16 v[50:53], v[192:195], v[200:203], v[50:53]
	v_mfma_f32_16x16x32_bf16 v[46:49], v[148:151], v[204:207], v[46:49]
	v_mfma_f32_16x16x32_bf16 v[46:49], v[164:167], v[208:211], v[46:49]
	v_mfma_f32_16x16x32_bf16 v[38:41], v[168:171], v[204:207], v[38:41]
	v_mfma_f32_16x16x32_bf16 v[38:41], v[172:175], v[208:211], v[38:41]
	v_mfma_f32_16x16x32_bf16 v[42:45], v[176:179], v[204:207], v[42:45]
	v_mfma_f32_16x16x32_bf16 v[42:45], v[184:187], v[208:211], v[42:45]
	v_mfma_f32_16x16x32_bf16 v[34:37], v[188:191], v[204:207], v[34:37]
	v_mfma_f32_16x16x32_bf16 v[34:37], v[192:195], v[208:211], v[34:37]
	v_mfma_f32_16x16x32_bf16 v[30:33], v[148:151], v[212:215], v[30:33]
	v_mfma_f32_16x16x32_bf16 v[30:33], v[164:167], v[216:219], v[30:33]
	v_mfma_f32_16x16x32_bf16 v[22:25], v[168:171], v[212:215], v[22:25]
	v_mfma_f32_16x16x32_bf16 v[22:25], v[172:175], v[216:219], v[22:25]
	v_mfma_f32_16x16x32_bf16 v[26:29], v[176:179], v[212:215], v[26:29]
	v_mfma_f32_16x16x32_bf16 v[26:29], v[184:187], v[216:219], v[26:29]
	v_mfma_f32_16x16x32_bf16 v[18:21], v[188:191], v[212:215], v[18:21]
	v_mfma_f32_16x16x32_bf16 v[18:21], v[192:195], v[216:219], v[18:21]
	v_mfma_f32_16x16x32_bf16 v[14:17], v[148:151], v[220:223], v[14:17]
	v_mfma_f32_16x16x32_bf16 v[14:17], v[164:167], v[224:227], v[14:17]
	v_mfma_f32_16x16x32_bf16 v[6:9], v[168:171], v[220:223], v[6:9]
	v_mfma_f32_16x16x32_bf16 v[6:9], v[172:175], v[224:227], v[6:9]
	v_mfma_f32_16x16x32_bf16 v[10:13], v[176:179], v[220:223], v[10:13]
	v_mfma_f32_16x16x32_bf16 v[10:13], v[184:187], v[224:227], v[10:13]
	v_mfma_f32_16x16x32_bf16 v[2:5], v[188:191], v[220:223], v[2:5]
	v_mfma_f32_16x16x32_bf16 v[2:5], v[192:195], v[224:227], v[2:5]
	s_barrier
	s_add_i32 s82, s82, 2
	s_add_u32 s6, s6, 0x100
	s_addc_u32 s7, s7, 0
	s_add_u32 s80, s80, 0x100
	s_addc_u32 s81, s81, 0
	s_cmp_gt_u32 s82, 61
	s_cbranch_scc0 .LBB0_2720
	s_setprio 0
	s_and_b64 vcc, exec, s[24:25]
	s_cbranch_vccz .LBB0_2723
	s_barrier

.LBB0_2805:
	ds_read_b128 v[130:133], v163
	ds_read_b128 v[134:137], v163 offset:1024
	ds_read_b128 v[138:141], v163 offset:2048
	ds_read_b128 v[142:145], v163 offset:3072
	ds_read_b128 v[146:149], v188
	ds_read_b128 v[150:153], v188 offset:1024
	ds_read_b128 v[174:177], v188 offset:2048
	ds_read_b128 v[178:181], v188 offset:3072
	s_add_u32 s28, s26, 0xffd50080
	s_addc_u32 s29, s27, -1
	s_cmpk_eq_i32 s62, 0xa8
	s_cselect_b32 s37, s7, s29
	s_cselect_b32 s36, s6, s28
	s_cselect_b32 s29, s25, s59
	s_cselect_b32 s28, s24, s12
	s_add_i32 m0, s38, 0xc000
	ds_read_b128 v[184:187], v189
	ds_read_b128 v[192:195], v189 offset:1024
	ds_read_b128 v[196:199], v189 offset:2048
	ds_read_b128 v[200:203], v189 offset:3072
	ds_read_b128 v[204:207], v189 offset:4096
	ds_read_b128 v[208:211], v189 offset:5120
	ds_read_b128 v[212:215], v189 offset:6144
	ds_read_b128 v[216:219], v189 offset:7168
	global_load_lds_dwordx4 v166, s[26:27]
	s_add_i32 m0, s38, 0xe000
	s_nop 0
	global_load_lds_dwordx4 v168, s[26:27]
	s_waitcnt vmcnt(8)
	s_waitcnt lgkmcnt(0)
	s_barrier
	v_mfma_f32_16x16x32_bf16 v[126:129], v[130:133], v[184:187], v[126:129]
	v_mfma_f32_16x16x32_bf16 v[126:129], v[134:137], v[192:195], v[126:129]
	v_mfma_f32_16x16x32_bf16 v[122:125], v[138:141], v[184:187], v[122:125]
	v_mfma_f32_16x16x32_bf16 v[122:125], v[142:145], v[192:195], v[122:125]
	v_mfma_f32_16x16x32_bf16 v[118:121], v[146:149], v[184:187], v[118:121]
	v_mfma_f32_16x16x32_bf16 v[118:121], v[150:153], v[192:195], v[118:121]
	v_mfma_f32_16x16x32_bf16 v[114:117], v[174:177], v[184:187], v[114:117]
	v_mfma_f32_16x16x32_bf16 v[114:117], v[178:181], v[192:195], v[114:117]
	v_mfma_f32_16x16x32_bf16 v[110:113], v[130:133], v[196:199], v[110:113]
	v_mfma_f32_16x16x32_bf16 v[110:113], v[134:137], v[200:203], v[110:113]
	v_mfma_f32_16x16x32_bf16 v[106:109], v[138:141], v[196:199], v[106:109]
	v_mfma_f32_16x16x32_bf16 v[106:109], v[142:145], v[200:203], v[106:109]
	v_mfma_f32_16x16x32_bf16 v[102:105], v[146:149], v[196:199], v[102:105]
	v_mfma_f32_16x16x32_bf16 v[102:105], v[150:153], v[200:203], v[102:105]
	v_mfma_f32_16x16x32_bf16 v[98:101], v[174:177], v[196:199], v[98:101]
	v_mfma_f32_16x16x32_bf16 v[98:101], v[178:181], v[200:203], v[98:101]
	v_mfma_f32_16x16x32_bf16 v[94:97], v[130:133], v[204:207], v[94:97]
	v_mfma_f32_16x16x32_bf16 v[94:97], v[134:137], v[208:211], v[94:97]
	v_mfma_f32_16x16x32_bf16 v[90:93], v[138:141], v[204:207], v[90:93]
	v_mfma_f32_16x16x32_bf16 v[90:93], v[142:145], v[208:211], v[90:93]
	v_mfma_f32_16x16x32_bf16 v[86:89], v[146:149], v[204:207], v[86:89]
	v_mfma_f32_16x16x32_bf16 v[86:89], v[150:153], v[208:211], v[86:89]
	v_mfma_f32_16x16x32_bf16 v[82:85], v[174:177], v[204:207], v[82:85]
	v_mfma_f32_16x16x32_bf16 v[82:85], v[178:181], v[208:211], v[82:85]
	v_mfma_f32_16x16x32_bf16 v[78:81], v[130:133], v[212:215], v[78:81]
	v_mfma_f32_16x16x32_bf16 v[78:81], v[134:137], v[216:219], v[78:81]
	v_mfma_f32_16x16x32_bf16 v[74:77], v[138:141], v[212:215], v[74:77]
	v_mfma_f32_16x16x32_bf16 v[74:77], v[142:145], v[216:219], v[74:77]
	v_mfma_f32_16x16x32_bf16 v[70:73], v[146:149], v[212:215], v[70:73]
	v_mfma_f32_16x16x32_bf16 v[70:73], v[150:153], v[216:219], v[70:73]
	v_mfma_f32_16x16x32_bf16 v[66:69], v[174:177], v[212:215], v[66:69]
	v_mfma_f32_16x16x32_bf16 v[66:69], v[178:181], v[216:219], v[66:69]
	s_barrier
	s_add_i32 s63, s47, s35
	s_add_u32 s98, s28, 0x80
	s_addc_u32 s99, s29, 0
	s_mov_b32 m0, s63
	ds_read_b128 v[184:187], v189 offset:16384
	ds_read_b128 v[192:195], v189 offset:17408
	ds_read_b128 v[196:199], v189 offset:18432
	ds_read_b128 v[200:203], v189 offset:19456
	ds_read_b128 v[204:207], v189 offset:20480
	ds_read_b128 v[208:211], v189 offset:21504
	ds_read_b128 v[212:215], v189 offset:22528
	ds_read_b128 v[216:219], v189 offset:23552
	global_load_lds_dwordx4 v156, s[28:29]
	s_add_i32 m0, s63, 0x2000
	s_add_u32 s66, s28, 0x2b0000
	s_addc_u32 s67, s29, 0
	s_add_i32 s63, s48, s35
	global_load_lds_dwordx4 v160, s[28:29]
	s_mov_b32 m0, s63
	global_load_lds_dwordx4 v156, s[66:67]
	s_add_i32 m0, s63, 0x2000
	s_nop 0
	global_load_lds_dwordx4 v160, s[66:67]
	s_add_u32 s100, s36, 0x80
	s_addc_u32 s101, s37, 0
	s_mov_b32 m0, s38
	s_nop 0
	global_load_lds_dwordx4 v154, s[36:37]
	s_mov_b32 m0, s39
	s_nop 0
	global_load_lds_dwordx4 v158, s[36:37]
	s_waitcnt vmcnt(8)
	s_waitcnt lgkmcnt(0)
	s_barrier
	v_mfma_f32_16x16x32_bf16 v[62:65], v[130:133], v[184:187], v[62:65]
	v_mfma_f32_16x16x32_bf16 v[62:65], v[134:137], v[192:195], v[62:65]
	v_mfma_f32_16x16x32_bf16 v[58:61], v[138:141], v[184:187], v[58:61]
	v_mfma_f32_16x16x32_bf16 v[58:61], v[142:145], v[192:195], v[58:61]
	v_mfma_f32_16x16x32_bf16 v[54:57], v[146:149], v[184:187], v[54:57]
	v_mfma_f32_16x16x32_bf16 v[54:57], v[150:153], v[192:195], v[54:57]
	v_mfma_f32_16x16x32_bf16 v[50:53], v[174:177], v[184:187], v[50:53]
	v_mfma_f32_16x16x32_bf16 v[50:53], v[178:181], v[192:195], v[50:53]
	v_mfma_f32_16x16x32_bf16 v[46:49], v[130:133], v[196:199], v[46:49]
	v_mfma_f32_16x16x32_bf16 v[46:49], v[134:137], v[200:203], v[46:49]
	v_mfma_f32_16x16x32_bf16 v[42:45], v[138:141], v[196:199], v[42:45]
	v_mfma_f32_16x16x32_bf16 v[42:45], v[142:145], v[200:203], v[42:45]
	v_mfma_f32_16x16x32_bf16 v[38:41], v[146:149], v[196:199], v[38:41]
	v_mfma_f32_16x16x32_bf16 v[38:41], v[150:153], v[200:203], v[38:41]
	v_mfma_f32_16x16x32_bf16 v[34:37], v[174:177], v[196:199], v[34:37]
	v_mfma_f32_16x16x32_bf16 v[34:37], v[178:181], v[200:203], v[34:37]
	v_mfma_f32_16x16x32_bf16 v[30:33], v[130:133], v[204:207], v[30:33]
	v_mfma_f32_16x16x32_bf16 v[30:33], v[134:137], v[208:211], v[30:33]
	v_mfma_f32_16x16x32_bf16 v[26:29], v[138:141], v[204:207], v[26:29]
	v_mfma_f32_16x16x32_bf16 v[26:29], v[142:145], v[208:211], v[26:29]
	v_mfma_f32_16x16x32_bf16 v[22:25], v[146:149], v[204:207], v[22:25]
	v_mfma_f32_16x16x32_bf16 v[22:25], v[150:153], v[208:211], v[22:25]
	v_mfma_f32_16x16x32_bf16 v[18:21], v[174:177], v[204:207], v[18:21]
	v_mfma_f32_16x16x32_bf16 v[18:21], v[178:181], v[208:211], v[18:21]
	v_mfma_f32_16x16x32_bf16 v[14:17], v[130:133], v[212:215], v[14:17]
	v_mfma_f32_16x16x32_bf16 v[14:17], v[134:137], v[216:219], v[14:17]
	v_mfma_f32_16x16x32_bf16 v[10:13], v[138:141], v[212:215], v[10:13]
	v_mfma_f32_16x16x32_bf16 v[10:13], v[142:145], v[216:219], v[10:13]
	v_mfma_f32_16x16x32_bf16 v[6:9], v[146:149], v[212:215], v[6:9]
	v_mfma_f32_16x16x32_bf16 v[6:9], v[150:153], v[216:219], v[6:9]
	v_mfma_f32_16x16x32_bf16 v[2:5], v[174:177], v[212:215], v[2:5]
	v_mfma_f32_16x16x32_bf16 v[2:5], v[178:181], v[216:219], v[2:5]
	s_barrier
	s_add_i32 s63, 0, 0x18000
	s_add_i32 s65, 0, 0x1c000
	ds_read_b128 v[130:133], v246
	ds_read_b128 v[134:137], v246 offset:1024
	ds_read_b128 v[138:141], v246 offset:2048
	ds_read_b128 v[142:145], v246 offset:3072
	ds_read_b128 v[146:149], v247
	ds_read_b128 v[150:153], v247 offset:1024
	ds_read_b128 v[174:177], v247 offset:2048
	ds_read_b128 v[178:181], v247 offset:3072
	s_add_u32 s36, s36, 0x2b0000
	s_addc_u32 s37, s37, 0
	s_mov_b32 m0, s40
	ds_read_b128 v[184:187], v189 offset:32768
	ds_read_b128 v[192:195], v189 offset:33792
	ds_read_b128 v[196:199], v189 offset:34816
	ds_read_b128 v[200:203], v189 offset:35840
	ds_read_b128 v[204:207], v189 offset:36864
	ds_read_b128 v[208:211], v189 offset:37888
	ds_read_b128 v[212:215], v189 offset:38912
	ds_read_b128 v[216:219], v189 offset:39936
	global_load_lds_dwordx4 v154, s[36:37]
	s_mov_b32 m0, s41
	s_nop 0
	global_load_lds_dwordx4 v158, s[36:37]
	s_waitcnt vmcnt(8)
	s_waitcnt lgkmcnt(0)
	s_barrier
	v_mfma_f32_16x16x32_bf16 v[126:129], v[130:133], v[184:187], v[126:129]
	v_mfma_f32_16x16x32_bf16 v[126:129], v[134:137], v[192:195], v[126:129]
	v_mfma_f32_16x16x32_bf16 v[122:125], v[138:141], v[184:187], v[122:125]
	v_mfma_f32_16x16x32_bf16 v[122:125], v[142:145], v[192:195], v[122:125]
	v_mfma_f32_16x16x32_bf16 v[118:121], v[146:149], v[184:187], v[118:121]
	v_mfma_f32_16x16x32_bf16 v[118:121], v[150:153], v[192:195], v[118:121]
	v_mfma_f32_16x16x32_bf16 v[114:117], v[174:177], v[184:187], v[114:117]
	v_mfma_f32_16x16x32_bf16 v[114:117], v[178:181], v[192:195], v[114:117]
	v_mfma_f32_16x16x32_bf16 v[110:113], v[130:133], v[196:199], v[110:113]
	v_mfma_f32_16x16x32_bf16 v[110:113], v[134:137], v[200:203], v[110:113]
	v_mfma_f32_16x16x32_bf16 v[106:109], v[138:141], v[196:199], v[106:109]
	v_mfma_f32_16x16x32_bf16 v[106:109], v[142:145], v[200:203], v[106:109]
	v_mfma_f32_16x16x32_bf16 v[102:105], v[146:149], v[196:199], v[102:105]
	v_mfma_f32_16x16x32_bf16 v[102:105], v[150:153], v[200:203], v[102:105]
	v_mfma_f32_16x16x32_bf16 v[98:101], v[174:177], v[196:199], v[98:101]
	v_mfma_f32_16x16x32_bf16 v[98:101], v[178:181], v[200:203], v[98:101]
	v_mfma_f32_16x16x32_bf16 v[94:97], v[130:133], v[204:207], v[94:97]
	v_mfma_f32_16x16x32_bf16 v[94:97], v[134:137], v[208:211], v[94:97]
	v_mfma_f32_16x16x32_bf16 v[90:93], v[138:141], v[204:207], v[90:93]
	v_mfma_f32_16x16x32_bf16 v[90:93], v[142:145], v[208:211], v[90:93]
	v_mfma_f32_16x16x32_bf16 v[86:89], v[146:149], v[204:207], v[86:89]
	v_mfma_f32_16x16x32_bf16 v[86:89], v[150:153], v[208:211], v[86:89]
	v_mfma_f32_16x16x32_bf16 v[82:85], v[174:177], v[204:207], v[82:85]
	v_mfma_f32_16x16x32_bf16 v[82:85], v[178:181], v[208:211], v[82:85]
	v_mfma_f32_16x16x32_bf16 v[78:81], v[130:133], v[212:215], v[78:81]
	v_mfma_f32_16x16x32_bf16 v[78:81], v[134:137], v[216:219], v[78:81]
	v_mfma_f32_16x16x32_bf16 v[74:77], v[138:141], v[212:215], v[74:77]
	v_mfma_f32_16x16x32_bf16 v[74:77], v[142:145], v[216:219], v[74:77]
	v_mfma_f32_16x16x32_bf16 v[70:73], v[146:149], v[212:215], v[70:73]
	v_mfma_f32_16x16x32_bf16 v[70:73], v[150:153], v[216:219], v[70:73]
	v_mfma_f32_16x16x32_bf16 v[66:69], v[174:177], v[212:215], v[66:69]
	v_mfma_f32_16x16x32_bf16 v[66:69], v[178:181], v[216:219], v[66:69]
	s_barrier
	s_add_i32 s36, s63, s35
	s_mov_b32 m0, s36
	ds_read_b128 v[184:187], v189 offset:49152
	ds_read_b128 v[192:195], v189 offset:50176
	ds_read_b128 v[196:199], v189 offset:51200
	ds_read_b128 v[200:203], v189 offset:52224
	ds_read_b128 v[204:207], v189 offset:53248
	ds_read_b128 v[208:211], v189 offset:54272
	ds_read_b128 v[212:215], v189 offset:55296
	ds_read_b128 v[216:219], v189 offset:56320
	global_load_lds_dwordx4 v156, s[98:99]
	s_add_i32 m0, s36, 0x2000
	s_add_u32 s28, s28, 0x2b0080
	s_addc_u32 s29, s29, 0
	s_add_i32 s36, s65, s35
	global_load_lds_dwordx4 v160, s[98:99]
	s_mov_b32 m0, s36
	s_nop 0
	global_load_lds_dwordx4 v156, s[28:29]
	s_add_i32 m0, s36, 0x2000
	s_nop 0
	global_load_lds_dwordx4 v160, s[28:29]
	s_mov_b32 m0, s43
	s_nop 0
	global_load_lds_dwordx4 v154, s[100:101]
	s_mov_b32 m0, s44
	s_nop 0
	global_load_lds_dwordx4 v158, s[100:101]
	s_waitcnt vmcnt(8)
	s_waitcnt lgkmcnt(0)
	s_barrier
	v_mfma_f32_16x16x32_bf16 v[62:65], v[130:133], v[184:187], v[62:65]
	v_mfma_f32_16x16x32_bf16 v[62:65], v[134:137], v[192:195], v[62:65]
	v_mfma_f32_16x16x32_bf16 v[58:61], v[138:141], v[184:187], v[58:61]
	v_mfma_f32_16x16x32_bf16 v[58:61], v[142:145], v[192:195], v[58:61]
	v_mfma_f32_16x16x32_bf16 v[54:57], v[146:149], v[184:187], v[54:57]
	v_mfma_f32_16x16x32_bf16 v[54:57], v[150:153], v[192:195], v[54:57]
	v_mfma_f32_16x16x32_bf16 v[50:53], v[174:177], v[184:187], v[50:53]
	v_mfma_f32_16x16x32_bf16 v[50:53], v[178:181], v[192:195], v[50:53]
	v_mfma_f32_16x16x32_bf16 v[46:49], v[130:133], v[196:199], v[46:49]
	v_mfma_f32_16x16x32_bf16 v[46:49], v[134:137], v[200:203], v[46:49]
	v_mfma_f32_16x16x32_bf16 v[42:45], v[138:141], v[196:199], v[42:45]
	v_mfma_f32_16x16x32_bf16 v[42:45], v[142:145], v[200:203], v[42:45]
	v_mfma_f32_16x16x32_bf16 v[38:41], v[146:149], v[196:199], v[38:41]
	v_mfma_f32_16x16x32_bf16 v[38:41], v[150:153], v[200:203], v[38:41]
	v_mfma_f32_16x16x32_bf16 v[34:37], v[174:177], v[196:199], v[34:37]
	v_mfma_f32_16x16x32_bf16 v[34:37], v[178:181], v[200:203], v[34:37]
	v_mfma_f32_16x16x32_bf16 v[30:33], v[130:133], v[204:207], v[30:33]
	v_mfma_f32_16x16x32_bf16 v[30:33], v[134:137], v[208:211], v[30:33]
	v_mfma_f32_16x16x32_bf16 v[26:29], v[138:141], v[204:207], v[26:29]
	v_mfma_f32_16x16x32_bf16 v[26:29], v[142:145], v[208:211], v[26:29]
	v_mfma_f32_16x16x32_bf16 v[22:25], v[146:149], v[204:207], v[22:25]
	v_mfma_f32_16x16x32_bf16 v[22:25], v[150:153], v[208:211], v[22:25]
	v_mfma_f32_16x16x32_bf16 v[18:21], v[174:177], v[204:207], v[18:21]
	v_mfma_f32_16x16x32_bf16 v[18:21], v[178:181], v[208:211], v[18:21]
	v_mfma_f32_16x16x32_bf16 v[14:17], v[130:133], v[212:215], v[14:17]
	v_mfma_f32_16x16x32_bf16 v[14:17], v[134:137], v[216:219], v[14:17]
	v_mfma_f32_16x16x32_bf16 v[10:13], v[138:141], v[212:215], v[10:13]
	v_mfma_f32_16x16x32_bf16 v[10:13], v[142:145], v[216:219], v[10:13]
	v_mfma_f32_16x16x32_bf16 v[6:9], v[146:149], v[212:215], v[6:9]
	v_mfma_f32_16x16x32_bf16 v[6:9], v[150:153], v[216:219], v[6:9]
	v_mfma_f32_16x16x32_bf16 v[2:5], v[174:177], v[212:215], v[2:5]
	v_mfma_f32_16x16x32_bf16 v[2:5], v[178:181], v[216:219], v[2:5]
	s_barrier
	s_add_i32 s62, s62, 2
	s_add_u32 s26, s26, 0x100
	s_addc_u32 s27, s27, 0
	s_add_u32 s12, s12, 0x100
	s_addc_u32 s59, s59, 0
	s_cmpk_gt_u32 s62, 0xa9
	s_cbranch_scc0 .LBB0_2805
	s_setprio 0
	s_and_b64 vcc, exec, s[22:23]
	s_cbranch_vccz .LBB0_2808
	s_barrier

	.amdhsa_kernel _Z9trunk_fwd4Args
		.amdhsa_group_segment_fixed_size 0
		.amdhsa_private_segment_fixed_size 0
		.amdhsa_kernarg_size 416
		.amdhsa_user_sgpr_count 2
		.amdhsa_user_sgpr_dispatch_ptr 0
		.amdhsa_user_sgpr_queue_ptr 0
		.amdhsa_user_sgpr_kernarg_segment_ptr 1
		.amdhsa_user_sgpr_dispatch_id 0
		.amdhsa_user_sgpr_kernarg_preload_length 0
		.amdhsa_user_sgpr_kernarg_preload_offset 0
		.amdhsa_user_sgpr_private_segment_size 0
		.amdhsa_uses_dynamic_stack 0
		.amdhsa_enable_private_segment 0
		.amdhsa_system_sgpr_workgroup_id_x 1
		.amdhsa_system_sgpr_workgroup_id_y 0
		.amdhsa_system_sgpr_workgroup_id_z 0
		.amdhsa_system_sgpr_workgroup_info 0
		.amdhsa_system_vgpr_workitem_id 0
		.amdhsa_next_free_vgpr 248
		.amdhsa_next_free_sgpr 102
		.amdhsa_accum_offset 248
		.amdhsa_reserve_vcc 1
		.amdhsa_float_round_mode_32 0
		.amdhsa_float_round_mode_16_64 0
		.amdhsa_float_denorm_mode_32 3
		.amdhsa_float_denorm_mode_16_64 3
		.amdhsa_dx10_clamp 1
		.amdhsa_ieee_mode 1
		.amdhsa_fp16_overflow 0
		.amdhsa_tg_split 0
		.amdhsa_exception_fp_ieee_invalid_op 0
		.amdhsa_exception_fp_denorm_src 0
		.amdhsa_exception_fp_ieee_div_zero 0
		.amdhsa_exception_fp_ieee_overflow 0
		.amdhsa_exception_fp_ieee_underflow 0
		.amdhsa_exception_fp_ieee_inexact 0
		.amdhsa_exception_int_div_zero 0
	.end_amdhsa_kernel

amdhsa.kernels:
  - .agpr_count:     0
    .args:
      - .offset:         0
        .size:           160
        .value_kind:     by_value
      - .offset:         160
        .size:           4
        .value_kind:     hidden_block_count_x
      - .offset:         164
        .size:           4
        .value_kind:     hidden_block_count_y
      - .offset:         168
        .size:           4
        .value_kind:     hidden_block_count_z
      - .offset:         172
        .size:           2
        .value_kind:     hidden_group_size_x
      - .offset:         174
        .size:           2
        .value_kind:     hidden_group_size_y
      - .offset:         176
        .size:           2
        .value_kind:     hidden_group_size_z
      - .offset:         178
        .size:           2
        .value_kind:     hidden_remainder_x
      - .offset:         180
        .size:           2
        .value_kind:     hidden_remainder_y
      - .offset:         182
        .size:           2
        .value_kind:     hidden_remainder_z
      - .offset:         200
        .size:           8
        .value_kind:     hidden_global_offset_x
      - .offset:         208
        .size:           8
        .value_kind:     hidden_global_offset_y
      - .offset:         216
        .size:           8
        .value_kind:     hidden_global_offset_z
      - .offset:         224
        .size:           2
        .value_kind:     hidden_grid_dims
      - .offset:         280
        .size:           4
        .value_kind:     hidden_dynamic_lds_size
    .group_segment_fixed_size: 0
    .kernarg_segment_align: 8
    .kernarg_segment_size: 416
    .language:       OpenCL C
    .language_version:
      - 2
      - 0
    .max_flat_workgroup_size: 512
    .name:           _Z9trunk_fwd4Args
    .private_segment_fixed_size: 0
    .sgpr_count:     108
    .sgpr_spill_count: 209
    .symbol:         _Z9trunk_fwd4Args.kd
    .uniform_work_group_size: 1
    .uses_dynamic_stack: false
    .vgpr_count:     248
    .vgpr_spill_count: 0
    .wavefront_size: 64
